# scalar-base LDS-DMA addressing in all K-loop load segments (no VALU address adds); SSD out-projection K-loop gets the same treatment as the others
# speedup vs baseline: 1.0307x; 1.0060x over previous
.LBB0_133:
	s_add_u32 vcc_lo, s0, 0xffffc000
	s_addc_u32 vcc_hi, s1, -1
	s_mov_b32 m0, s52
	s_nop 0
	global_load_lds_dwordx4 v158, vcc
	s_mov_b32 m0, s53
	s_nop 0
	global_load_lds_dwordx4 v160, vcc
	ds_read_b128 v[130:133], v224
	ds_read_b128 v[134:137], v224 offset:1024
	ds_read_b128 v[138:141], v224 offset:2048
	ds_read_b128 v[142:145], v224 offset:3072
	ds_read_b128 v[146:149], v224 offset:16384
	ds_read_b128 v[162:165], v224 offset:17408
	ds_read_b128 v[166:169], v224 offset:18432
	ds_read_b128 v[170:173], v224 offset:19456
	ds_read_b128 v[174:177], v225
	ds_read_b128 v[178:181], v225 offset:1024
	ds_read_b128 v[182:185], v225 offset:2048
	ds_read_b128 v[186:189], v225 offset:3072
	ds_read_b128 v[190:193], v225 offset:4096
	ds_read_b128 v[204:207], v225 offset:5120
	ds_read_b128 v[208:211], v225 offset:6144
	ds_read_b128 v[212:215], v225 offset:7168
	s_add_u32 s4, s0, 0x100
	s_addc_u32 s5, s1, 0
	s_add_i32 s58, 0, 0x10000
	s_cmp_eq_u32 s57, 28
	s_cselect_b32 s35, s27, s5
	s_cselect_b32 s34, s26, s4
	s_cselect_b32 s31, s25, s51
	s_cselect_b32 s30, s37, s50
	s_add_i32 s59, 0, 0x14000
	s_add_i32 m0, s38, 0xc000
	s_nop 0
	global_load_lds_dwordx4 v158, s[0:1]
	s_add_i32 m0, s38, 0xe000
	s_nop 0
	global_load_lds_dwordx4 v160, s[0:1]
	s_waitcnt vmcnt(8)
	s_waitcnt lgkmcnt(0)
	v_mfma_f32_16x16x32_bf16 v[126:129], v[130:133], v[174:177], v[126:129]
	v_mfma_f32_16x16x32_bf16 v[126:129], v[134:137], v[178:181], v[126:129]
	s_barrier
	s_setprio 1
	v_mfma_f32_16x16x32_bf16 v[122:125], v[142:145], v[178:181], v[122:125]
	v_mfma_f32_16x16x32_bf16 v[122:125], v[138:141], v[174:177], v[122:125]
	v_mfma_f32_16x16x32_bf16 v[106:109], v[138:141], v[182:185], v[106:109]
	v_mfma_f32_16x16x32_bf16 v[106:109], v[142:145], v[186:189], v[106:109]
	v_mfma_f32_16x16x32_bf16 v[110:113], v[134:137], v[186:189], v[110:113]
	v_mfma_f32_16x16x32_bf16 v[110:113], v[130:133], v[182:185], v[110:113]
	v_mfma_f32_16x16x32_bf16 v[94:97], v[130:133], v[190:193], v[94:97]
	v_mfma_f32_16x16x32_bf16 v[94:97], v[134:137], v[204:207], v[94:97]
	v_mfma_f32_16x16x32_bf16 v[90:93], v[142:145], v[204:207], v[90:93]
	v_mfma_f32_16x16x32_bf16 v[90:93], v[138:141], v[190:193], v[90:93]
	v_mfma_f32_16x16x32_bf16 v[74:77], v[138:141], v[208:211], v[74:77]
	v_mfma_f32_16x16x32_bf16 v[74:77], v[142:145], v[212:215], v[74:77]
	v_mfma_f32_16x16x32_bf16 v[78:81], v[134:137], v[212:215], v[78:81]
	v_mfma_f32_16x16x32_bf16 v[78:81], v[130:133], v[208:211], v[78:81]
	v_mfma_f32_16x16x32_bf16 v[118:121], v[146:149], v[174:177], v[118:121]
	v_mfma_f32_16x16x32_bf16 v[118:121], v[162:165], v[178:181], v[118:121]
	v_mfma_f32_16x16x32_bf16 v[114:117], v[170:173], v[178:181], v[114:117]
	v_mfma_f32_16x16x32_bf16 v[114:117], v[166:169], v[174:177], v[114:117]
	v_mfma_f32_16x16x32_bf16 v[98:101], v[166:169], v[182:185], v[98:101]
	v_mfma_f32_16x16x32_bf16 v[98:101], v[170:173], v[186:189], v[98:101]
	v_mfma_f32_16x16x32_bf16 v[102:105], v[162:165], v[186:189], v[102:105]
	v_mfma_f32_16x16x32_bf16 v[102:105], v[146:149], v[182:185], v[102:105]
	v_mfma_f32_16x16x32_bf16 v[86:89], v[146:149], v[190:193], v[86:89]
	v_mfma_f32_16x16x32_bf16 v[86:89], v[162:165], v[204:207], v[86:89]
	v_mfma_f32_16x16x32_bf16 v[82:85], v[170:173], v[204:207], v[82:85]
	v_mfma_f32_16x16x32_bf16 v[82:85], v[166:169], v[190:193], v[82:85]
	v_mfma_f32_16x16x32_bf16 v[66:69], v[166:169], v[208:211], v[66:69]
	v_mfma_f32_16x16x32_bf16 v[66:69], v[170:173], v[212:215], v[66:69]
	v_mfma_f32_16x16x32_bf16 v[70:73], v[162:165], v[212:215], v[70:73]
	v_mfma_f32_16x16x32_bf16 v[70:73], v[146:149], v[208:211], v[70:73]
	s_setprio 0
	s_barrier
	ds_read_b128 v[174:177], v225 offset:16384
	ds_read_b128 v[178:181], v225 offset:17408
	ds_read_b128 v[182:185], v225 offset:18432
	ds_read_b128 v[186:189], v225 offset:19456
	ds_read_b128 v[190:193], v225 offset:20480
	ds_read_b128 v[204:207], v225 offset:21504
	ds_read_b128 v[208:211], v225 offset:22528
	ds_read_b128 v[212:215], v225 offset:23552
	s_add_i32 s0, s58, s15
	s_mov_b32 m0, s0
	s_nop 0
	global_load_lds_dwordx4 v152, s[30:31]
	s_add_i32 m0, s0, 0x2000
	s_add_u32 s0, s30, 0x80000
	s_addc_u32 s1, s31, 0
	s_add_i32 s58, s59, s15
	global_load_lds_dwordx4 v156, s[30:31]
	s_mov_b32 m0, s58
	s_nop 0
	global_load_lds_dwordx4 v152, s[0:1]
	s_add_i32 m0, s58, 0x2000
	s_nop 0
	global_load_lds_dwordx4 v156, s[0:1]
	s_waitcnt vmcnt(6)
	s_waitcnt lgkmcnt(0)
	v_mfma_f32_16x16x32_bf16 v[62:65], v[130:133], v[174:177], v[62:65]
	v_mfma_f32_16x16x32_bf16 v[62:65], v[134:137], v[178:181], v[62:65]
	s_barrier
	s_setprio 1
	v_mfma_f32_16x16x32_bf16 v[58:61], v[142:145], v[178:181], v[58:61]
	v_mfma_f32_16x16x32_bf16 v[58:61], v[138:141], v[174:177], v[58:61]
	v_mfma_f32_16x16x32_bf16 v[42:45], v[138:141], v[182:185], v[42:45]
	v_mfma_f32_16x16x32_bf16 v[42:45], v[142:145], v[186:189], v[42:45]
	v_mfma_f32_16x16x32_bf16 v[46:49], v[134:137], v[186:189], v[46:49]
	v_mfma_f32_16x16x32_bf16 v[46:49], v[130:133], v[182:185], v[46:49]
	v_mfma_f32_16x16x32_bf16 v[30:33], v[130:133], v[190:193], v[30:33]
	v_mfma_f32_16x16x32_bf16 v[30:33], v[134:137], v[204:207], v[30:33]
	v_mfma_f32_16x16x32_bf16 v[26:29], v[142:145], v[204:207], v[26:29]
	v_mfma_f32_16x16x32_bf16 v[26:29], v[138:141], v[190:193], v[26:29]
	v_mfma_f32_16x16x32_bf16 v[10:13], v[138:141], v[208:211], v[10:13]
	v_mfma_f32_16x16x32_bf16 v[10:13], v[142:145], v[212:215], v[10:13]
	v_mfma_f32_16x16x32_bf16 v[14:17], v[134:137], v[212:215], v[14:17]
	v_mfma_f32_16x16x32_bf16 v[14:17], v[130:133], v[208:211], v[14:17]
	v_mfma_f32_16x16x32_bf16 v[54:57], v[146:149], v[174:177], v[54:57]
	v_mfma_f32_16x16x32_bf16 v[54:57], v[162:165], v[178:181], v[54:57]
	v_mfma_f32_16x16x32_bf16 v[50:53], v[170:173], v[178:181], v[50:53]
	v_mfma_f32_16x16x32_bf16 v[50:53], v[166:169], v[174:177], v[50:53]
	v_mfma_f32_16x16x32_bf16 v[34:37], v[166:169], v[182:185], v[34:37]
	v_mfma_f32_16x16x32_bf16 v[34:37], v[170:173], v[186:189], v[34:37]
	v_mfma_f32_16x16x32_bf16 v[38:41], v[162:165], v[186:189], v[38:41]
	v_mfma_f32_16x16x32_bf16 v[38:41], v[146:149], v[182:185], v[38:41]
	v_mfma_f32_16x16x32_bf16 v[22:25], v[146:149], v[190:193], v[22:25]
	v_mfma_f32_16x16x32_bf16 v[22:25], v[162:165], v[204:207], v[22:25]
	v_mfma_f32_16x16x32_bf16 v[18:21], v[170:173], v[204:207], v[18:21]
	v_mfma_f32_16x16x32_bf16 v[18:21], v[166:169], v[190:193], v[18:21]
	v_mfma_f32_16x16x32_bf16 v[2:5], v[166:169], v[208:211], v[2:5]
	v_mfma_f32_16x16x32_bf16 v[2:5], v[170:173], v[212:215], v[2:5]
	v_mfma_f32_16x16x32_bf16 v[6:9], v[162:165], v[212:215], v[6:9]
	v_mfma_f32_16x16x32_bf16 v[6:9], v[146:149], v[208:211], v[6:9]
	s_setprio 0
	s_barrier
	s_mov_b32 m0, s38
	s_nop 0
	global_load_lds_dwordx4 v150, s[34:35]
	s_mov_b32 m0, s39
	s_nop 0
	global_load_lds_dwordx4 v154, s[34:35]
	ds_read_b128 v[130:133], v224 offset:32768
	ds_read_b128 v[134:137], v224 offset:33792
	ds_read_b128 v[138:141], v224 offset:34816
	ds_read_b128 v[142:145], v224 offset:35840
	ds_read_b128 v[146:149], v224 offset:49152
	ds_read_b128 v[162:165], v224 offset:50176
	ds_read_b128 v[166:169], v224 offset:51200
	ds_read_b128 v[170:173], v224 offset:52224
	ds_read_b128 v[174:177], v225 offset:32768
	ds_read_b128 v[178:181], v225 offset:33792
	ds_read_b128 v[182:185], v225 offset:34816
	ds_read_b128 v[186:189], v225 offset:35840
	ds_read_b128 v[190:193], v225 offset:36864
	ds_read_b128 v[204:207], v225 offset:37888
	ds_read_b128 v[208:211], v225 offset:38912
	ds_read_b128 v[212:215], v225 offset:39936
	s_add_i32 s58, 0, 0x18000
	s_add_i32 s59, 0, 0x1c000
	s_add_u32 s0, s34, 0x4000
	s_addc_u32 s1, s35, 0
	s_mov_b32 m0, s40
	s_nop 0
	global_load_lds_dwordx4 v150, s[0:1]
	s_mov_b32 m0, s41
	s_nop 0
	global_load_lds_dwordx4 v154, s[0:1]
	s_waitcnt vmcnt(8)
	s_waitcnt lgkmcnt(0)
	v_mfma_f32_16x16x32_bf16 v[126:129], v[130:133], v[174:177], v[126:129]
	v_mfma_f32_16x16x32_bf16 v[126:129], v[134:137], v[178:181], v[126:129]
	s_barrier
	s_setprio 1
	v_mfma_f32_16x16x32_bf16 v[122:125], v[142:145], v[178:181], v[122:125]
	v_mfma_f32_16x16x32_bf16 v[122:125], v[138:141], v[174:177], v[122:125]
	v_mfma_f32_16x16x32_bf16 v[106:109], v[138:141], v[182:185], v[106:109]
	v_mfma_f32_16x16x32_bf16 v[106:109], v[142:145], v[186:189], v[106:109]
	v_mfma_f32_16x16x32_bf16 v[110:113], v[134:137], v[186:189], v[110:113]
	v_mfma_f32_16x16x32_bf16 v[110:113], v[130:133], v[182:185], v[110:113]
	v_mfma_f32_16x16x32_bf16 v[94:97], v[130:133], v[190:193], v[94:97]
	v_mfma_f32_16x16x32_bf16 v[94:97], v[134:137], v[204:207], v[94:97]
	v_mfma_f32_16x16x32_bf16 v[90:93], v[142:145], v[204:207], v[90:93]
	v_mfma_f32_16x16x32_bf16 v[90:93], v[138:141], v[190:193], v[90:93]
	v_mfma_f32_16x16x32_bf16 v[74:77], v[138:141], v[208:211], v[74:77]
	v_mfma_f32_16x16x32_bf16 v[74:77], v[142:145], v[212:215], v[74:77]
	v_mfma_f32_16x16x32_bf16 v[78:81], v[134:137], v[212:215], v[78:81]
	v_mfma_f32_16x16x32_bf16 v[78:81], v[130:133], v[208:211], v[78:81]
	v_mfma_f32_16x16x32_bf16 v[118:121], v[146:149], v[174:177], v[118:121]
	v_mfma_f32_16x16x32_bf16 v[118:121], v[162:165], v[178:181], v[118:121]
	v_mfma_f32_16x16x32_bf16 v[114:117], v[170:173], v[178:181], v[114:117]
	v_mfma_f32_16x16x32_bf16 v[114:117], v[166:169], v[174:177], v[114:117]
	v_mfma_f32_16x16x32_bf16 v[98:101], v[166:169], v[182:185], v[98:101]
	v_mfma_f32_16x16x32_bf16 v[98:101], v[170:173], v[186:189], v[98:101]
	v_mfma_f32_16x16x32_bf16 v[102:105], v[162:165], v[186:189], v[102:105]
	v_mfma_f32_16x16x32_bf16 v[102:105], v[146:149], v[182:185], v[102:105]
	v_mfma_f32_16x16x32_bf16 v[86:89], v[146:149], v[190:193], v[86:89]
	v_mfma_f32_16x16x32_bf16 v[86:89], v[162:165], v[204:207], v[86:89]
	v_mfma_f32_16x16x32_bf16 v[82:85], v[170:173], v[204:207], v[82:85]
	v_mfma_f32_16x16x32_bf16 v[82:85], v[166:169], v[190:193], v[82:85]
	v_mfma_f32_16x16x32_bf16 v[66:69], v[166:169], v[208:211], v[66:69]
	v_mfma_f32_16x16x32_bf16 v[66:69], v[170:173], v[212:215], v[66:69]
	v_mfma_f32_16x16x32_bf16 v[70:73], v[162:165], v[212:215], v[70:73]
	v_mfma_f32_16x16x32_bf16 v[70:73], v[146:149], v[208:211], v[70:73]
	s_setprio 0
	s_barrier
	ds_read_b128 v[174:177], v225 offset:49152
	ds_read_b128 v[178:181], v225 offset:50176
	ds_read_b128 v[182:185], v225 offset:51200
	ds_read_b128 v[186:189], v225 offset:52224
	ds_read_b128 v[190:193], v225 offset:53248
	ds_read_b128 v[204:207], v225 offset:54272
	ds_read_b128 v[208:211], v225 offset:55296
	ds_read_b128 v[212:215], v225 offset:56320
	s_add_i32 s0, s58, s15
	s_add_u32 vcc_lo, s30, s94
	s_addc_u32 vcc_hi, s31, s95
	s_mov_b32 m0, s0
	s_nop 0
	global_load_lds_dwordx4 v152, vcc
	s_add_i32 m0, s0, 0x2000
	s_add_u32 s0, s30, 0x80080
	s_addc_u32 s1, s31, 0
	s_add_i32 s30, s59, s15
	global_load_lds_dwordx4 v156, vcc
	s_mov_b32 m0, s30
	s_nop 0
	global_load_lds_dwordx4 v152, s[0:1]
	s_add_i32 m0, s30, 0x2000
	s_nop 0
	global_load_lds_dwordx4 v156, s[0:1]
	s_waitcnt vmcnt(6)
	s_waitcnt lgkmcnt(0)
	v_mfma_f32_16x16x32_bf16 v[62:65], v[130:133], v[174:177], v[62:65]
	v_mfma_f32_16x16x32_bf16 v[62:65], v[134:137], v[178:181], v[62:65]
	s_barrier
	s_setprio 1
	v_mfma_f32_16x16x32_bf16 v[58:61], v[142:145], v[178:181], v[58:61]
	v_mfma_f32_16x16x32_bf16 v[58:61], v[138:141], v[174:177], v[58:61]
	v_mfma_f32_16x16x32_bf16 v[42:45], v[138:141], v[182:185], v[42:45]
	v_mfma_f32_16x16x32_bf16 v[42:45], v[142:145], v[186:189], v[42:45]
	v_mfma_f32_16x16x32_bf16 v[46:49], v[134:137], v[186:189], v[46:49]
	v_mfma_f32_16x16x32_bf16 v[46:49], v[130:133], v[182:185], v[46:49]
	v_mfma_f32_16x16x32_bf16 v[30:33], v[130:133], v[190:193], v[30:33]
	v_mfma_f32_16x16x32_bf16 v[30:33], v[134:137], v[204:207], v[30:33]
	v_mfma_f32_16x16x32_bf16 v[26:29], v[142:145], v[204:207], v[26:29]
	v_mfma_f32_16x16x32_bf16 v[26:29], v[138:141], v[190:193], v[26:29]
	v_mfma_f32_16x16x32_bf16 v[10:13], v[138:141], v[208:211], v[10:13]
	v_mfma_f32_16x16x32_bf16 v[10:13], v[142:145], v[212:215], v[10:13]
	s_add_i32 s57, s57, 2
	v_mfma_f32_16x16x32_bf16 v[14:17], v[134:137], v[212:215], v[14:17]
	v_mfma_f32_16x16x32_bf16 v[14:17], v[130:133], v[208:211], v[14:17]
	s_add_u32 s50, s50, 0x100
	v_mfma_f32_16x16x32_bf16 v[54:57], v[146:149], v[174:177], v[54:57]
	v_mfma_f32_16x16x32_bf16 v[54:57], v[162:165], v[178:181], v[54:57]
	s_addc_u32 s51, s51, 0
	v_mfma_f32_16x16x32_bf16 v[50:53], v[170:173], v[178:181], v[50:53]
	v_mfma_f32_16x16x32_bf16 v[50:53], v[166:169], v[174:177], v[50:53]
	s_cmp_gt_u32 s57, 29
	v_mfma_f32_16x16x32_bf16 v[34:37], v[166:169], v[182:185], v[34:37]
	v_mfma_f32_16x16x32_bf16 v[34:37], v[170:173], v[186:189], v[34:37]
	s_mov_b64 s[0:1], s[4:5]
	v_mfma_f32_16x16x32_bf16 v[38:41], v[162:165], v[186:189], v[38:41]
	v_mfma_f32_16x16x32_bf16 v[38:41], v[146:149], v[182:185], v[38:41]
	v_mfma_f32_16x16x32_bf16 v[22:25], v[146:149], v[190:193], v[22:25]
	v_mfma_f32_16x16x32_bf16 v[22:25], v[162:165], v[204:207], v[22:25]
	v_mfma_f32_16x16x32_bf16 v[18:21], v[170:173], v[204:207], v[18:21]
	v_mfma_f32_16x16x32_bf16 v[18:21], v[166:169], v[190:193], v[18:21]
	v_mfma_f32_16x16x32_bf16 v[2:5], v[166:169], v[208:211], v[2:5]
	v_mfma_f32_16x16x32_bf16 v[2:5], v[170:173], v[212:215], v[2:5]
	v_mfma_f32_16x16x32_bf16 v[6:9], v[162:165], v[212:215], v[6:9]
	v_mfma_f32_16x16x32_bf16 v[6:9], v[146:149], v[208:211], v[6:9]
	s_setprio 0
	s_barrier
	s_cbranch_scc0 .LBB0_133
	s_and_b64 vcc, exec, s[16:17]
	s_cbranch_vccz .LBB0_136
	s_barrier

.LBB0_305:
	s_add_u32 vcc_lo, s0, 0xffffc000
	s_addc_u32 vcc_hi, s1, -1
	s_mov_b32 m0, s62
	s_nop 0
	global_load_lds_dwordx4 v178, vcc
	s_mov_b32 m0, s63
	s_nop 0
	global_load_lds_dwordx4 v180, vcc
	ds_read_b128 v[130:133], v226
	ds_read_b128 v[134:137], v226 offset:1024
	ds_read_b128 v[138:141], v226 offset:2048
	ds_read_b128 v[142:145], v226 offset:3072
	ds_read_b128 v[146:149], v226 offset:16384
	ds_read_b128 v[150:153], v226 offset:17408
	ds_read_b128 v[154:157], v226 offset:18432
	ds_read_b128 v[158:161], v226 offset:19456
	ds_read_b128 v[162:165], v227
	ds_read_b128 v[166:169], v227 offset:1024
	ds_read_b128 v[182:185], v227 offset:2048
	ds_read_b128 v[186:189], v227 offset:3072
	ds_read_b128 v[190:193], v227 offset:4096
	ds_read_b128 v[204:207], v227 offset:5120
	ds_read_b128 v[208:211], v227 offset:6144
	ds_read_b128 v[212:215], v227 offset:7168
	s_add_i32 s71, s38, 2
	s_add_u32 s4, s0, 0x100
	s_addc_u32 s5, s1, 0
	s_add_i32 s73, 0, 0x10000
	s_cmp_eq_u32 s37, s38
	s_cselect_b32 s41, s31, s5
	s_cselect_b32 s40, s30, s4
	s_cselect_b32 s39, s25, s70
	s_cselect_b32 s38, s27, s51
	s_add_i32 s75, 0, 0x14000
	s_add_i32 m0, s56, 0xc000
	s_nop 0
	global_load_lds_dwordx4 v178, s[0:1]
	s_add_i32 m0, s56, 0xe000
	s_nop 0
	global_load_lds_dwordx4 v180, s[0:1]
	s_waitcnt vmcnt(8)
	s_waitcnt lgkmcnt(0)
	v_mfma_f32_16x16x32_bf16 v[126:129], v[130:133], v[162:165], v[126:129]
	v_mfma_f32_16x16x32_bf16 v[126:129], v[134:137], v[166:169], v[126:129]
	s_barrier
	s_setprio 1
	v_mfma_f32_16x16x32_bf16 v[122:125], v[142:145], v[166:169], v[122:125]
	v_mfma_f32_16x16x32_bf16 v[122:125], v[138:141], v[162:165], v[122:125]
	v_mfma_f32_16x16x32_bf16 v[106:109], v[138:141], v[182:185], v[106:109]
	v_mfma_f32_16x16x32_bf16 v[106:109], v[142:145], v[186:189], v[106:109]
	v_mfma_f32_16x16x32_bf16 v[110:113], v[134:137], v[186:189], v[110:113]
	v_mfma_f32_16x16x32_bf16 v[110:113], v[130:133], v[182:185], v[110:113]
	v_mfma_f32_16x16x32_bf16 v[94:97], v[130:133], v[190:193], v[94:97]
	v_mfma_f32_16x16x32_bf16 v[94:97], v[134:137], v[204:207], v[94:97]
	v_mfma_f32_16x16x32_bf16 v[90:93], v[142:145], v[204:207], v[90:93]
	v_mfma_f32_16x16x32_bf16 v[90:93], v[138:141], v[190:193], v[90:93]
	v_mfma_f32_16x16x32_bf16 v[74:77], v[138:141], v[208:211], v[74:77]
	v_mfma_f32_16x16x32_bf16 v[74:77], v[142:145], v[212:215], v[74:77]
	v_mfma_f32_16x16x32_bf16 v[78:81], v[134:137], v[212:215], v[78:81]
	v_mfma_f32_16x16x32_bf16 v[78:81], v[130:133], v[208:211], v[78:81]
	v_mfma_f32_16x16x32_bf16 v[118:121], v[146:149], v[162:165], v[118:121]
	v_mfma_f32_16x16x32_bf16 v[118:121], v[150:153], v[166:169], v[118:121]
	v_mfma_f32_16x16x32_bf16 v[114:117], v[158:161], v[166:169], v[114:117]
	v_mfma_f32_16x16x32_bf16 v[114:117], v[154:157], v[162:165], v[114:117]
	v_mfma_f32_16x16x32_bf16 v[98:101], v[154:157], v[182:185], v[98:101]
	v_mfma_f32_16x16x32_bf16 v[98:101], v[158:161], v[186:189], v[98:101]
	v_mfma_f32_16x16x32_bf16 v[102:105], v[150:153], v[186:189], v[102:105]
	v_mfma_f32_16x16x32_bf16 v[102:105], v[146:149], v[182:185], v[102:105]
	v_mfma_f32_16x16x32_bf16 v[86:89], v[146:149], v[190:193], v[86:89]
	v_mfma_f32_16x16x32_bf16 v[86:89], v[150:153], v[204:207], v[86:89]
	v_mfma_f32_16x16x32_bf16 v[82:85], v[158:161], v[204:207], v[82:85]
	v_mfma_f32_16x16x32_bf16 v[82:85], v[154:157], v[190:193], v[82:85]
	v_mfma_f32_16x16x32_bf16 v[66:69], v[154:157], v[208:211], v[66:69]
	v_mfma_f32_16x16x32_bf16 v[66:69], v[158:161], v[212:215], v[66:69]
	v_mfma_f32_16x16x32_bf16 v[70:73], v[150:153], v[212:215], v[70:73]
	v_mfma_f32_16x16x32_bf16 v[70:73], v[146:149], v[208:211], v[70:73]
	s_setprio 0
	s_barrier
	ds_read_b128 v[162:165], v227 offset:16384
	ds_read_b128 v[166:169], v227 offset:17408
	ds_read_b128 v[182:185], v227 offset:18432
	ds_read_b128 v[186:189], v227 offset:19456
	ds_read_b128 v[190:193], v227 offset:20480
	ds_read_b128 v[204:207], v227 offset:21504
	ds_read_b128 v[208:211], v227 offset:22528
	ds_read_b128 v[212:215], v227 offset:23552
	s_add_i32 s0, s73, s15
	s_mov_b32 m0, s0
	s_nop 0
	global_load_lds_dwordx4 v172, s[38:39]
	s_add_i32 m0, s0, 0x2000
	s_add_u32 s0, s38, 0x80000
	s_addc_u32 s1, s39, 0
	s_add_i32 s73, s75, s15
	global_load_lds_dwordx4 v176, s[38:39]
	s_mov_b32 m0, s73
	s_nop 0
	global_load_lds_dwordx4 v172, s[0:1]
	s_add_i32 m0, s73, 0x2000
	s_nop 0
	global_load_lds_dwordx4 v176, s[0:1]
	s_waitcnt vmcnt(6)
	s_waitcnt lgkmcnt(0)
	v_mfma_f32_16x16x32_bf16 v[62:65], v[130:133], v[162:165], v[62:65]
	v_mfma_f32_16x16x32_bf16 v[62:65], v[134:137], v[166:169], v[62:65]
	s_barrier
	s_setprio 1
	v_mfma_f32_16x16x32_bf16 v[58:61], v[142:145], v[166:169], v[58:61]
	v_mfma_f32_16x16x32_bf16 v[58:61], v[138:141], v[162:165], v[58:61]
	v_mfma_f32_16x16x32_bf16 v[42:45], v[138:141], v[182:185], v[42:45]
	v_mfma_f32_16x16x32_bf16 v[42:45], v[142:145], v[186:189], v[42:45]
	v_mfma_f32_16x16x32_bf16 v[46:49], v[134:137], v[186:189], v[46:49]
	v_mfma_f32_16x16x32_bf16 v[46:49], v[130:133], v[182:185], v[46:49]
	v_mfma_f32_16x16x32_bf16 v[30:33], v[130:133], v[190:193], v[30:33]
	v_mfma_f32_16x16x32_bf16 v[30:33], v[134:137], v[204:207], v[30:33]
	v_mfma_f32_16x16x32_bf16 v[26:29], v[142:145], v[204:207], v[26:29]
	v_mfma_f32_16x16x32_bf16 v[26:29], v[138:141], v[190:193], v[26:29]
	v_mfma_f32_16x16x32_bf16 v[10:13], v[138:141], v[208:211], v[10:13]
	v_mfma_f32_16x16x32_bf16 v[10:13], v[142:145], v[212:215], v[10:13]
	v_mfma_f32_16x16x32_bf16 v[14:17], v[134:137], v[212:215], v[14:17]
	v_mfma_f32_16x16x32_bf16 v[14:17], v[130:133], v[208:211], v[14:17]
	v_mfma_f32_16x16x32_bf16 v[54:57], v[146:149], v[162:165], v[54:57]
	v_mfma_f32_16x16x32_bf16 v[54:57], v[150:153], v[166:169], v[54:57]
	v_mfma_f32_16x16x32_bf16 v[50:53], v[158:161], v[166:169], v[50:53]
	v_mfma_f32_16x16x32_bf16 v[50:53], v[154:157], v[162:165], v[50:53]
	v_mfma_f32_16x16x32_bf16 v[34:37], v[154:157], v[182:185], v[34:37]
	v_mfma_f32_16x16x32_bf16 v[34:37], v[158:161], v[186:189], v[34:37]
	v_mfma_f32_16x16x32_bf16 v[38:41], v[150:153], v[186:189], v[38:41]
	v_mfma_f32_16x16x32_bf16 v[38:41], v[146:149], v[182:185], v[38:41]
	v_mfma_f32_16x16x32_bf16 v[22:25], v[146:149], v[190:193], v[22:25]
	v_mfma_f32_16x16x32_bf16 v[22:25], v[150:153], v[204:207], v[22:25]
	v_mfma_f32_16x16x32_bf16 v[18:21], v[158:161], v[204:207], v[18:21]
	v_mfma_f32_16x16x32_bf16 v[18:21], v[154:157], v[190:193], v[18:21]
	v_mfma_f32_16x16x32_bf16 v[2:5], v[154:157], v[208:211], v[2:5]
	v_mfma_f32_16x16x32_bf16 v[2:5], v[158:161], v[212:215], v[2:5]
	v_mfma_f32_16x16x32_bf16 v[6:9], v[150:153], v[212:215], v[6:9]
	v_mfma_f32_16x16x32_bf16 v[6:9], v[146:149], v[208:211], v[6:9]
	s_setprio 0
	s_barrier
	s_mov_b32 m0, s56
	s_nop 0
	global_load_lds_dwordx4 v170, s[40:41]
	s_mov_b32 m0, s57
	s_nop 0
	global_load_lds_dwordx4 v174, s[40:41]
	ds_read_b128 v[130:133], v226 offset:32768
	ds_read_b128 v[134:137], v226 offset:33792
	ds_read_b128 v[138:141], v226 offset:34816
	ds_read_b128 v[142:145], v226 offset:35840
	ds_read_b128 v[146:149], v226 offset:49152
	ds_read_b128 v[150:153], v226 offset:50176
	ds_read_b128 v[154:157], v226 offset:51200
	ds_read_b128 v[158:161], v226 offset:52224
	ds_read_b128 v[162:165], v227 offset:32768
	ds_read_b128 v[166:169], v227 offset:33792
	ds_read_b128 v[182:185], v227 offset:34816
	ds_read_b128 v[186:189], v227 offset:35840
	ds_read_b128 v[190:193], v227 offset:36864
	ds_read_b128 v[204:207], v227 offset:37888
	ds_read_b128 v[208:211], v227 offset:38912
	ds_read_b128 v[212:215], v227 offset:39936
	s_add_i32 s73, 0, 0x18000
	s_add_i32 s75, 0, 0x1c000
	s_add_u32 s0, s40, 0x4000
	s_addc_u32 s1, s41, 0
	s_mov_b32 m0, s58
	s_nop 0
	global_load_lds_dwordx4 v170, s[0:1]
	s_mov_b32 m0, s59
	s_nop 0
	global_load_lds_dwordx4 v174, s[0:1]
	s_waitcnt vmcnt(8)
	s_waitcnt lgkmcnt(0)
	v_mfma_f32_16x16x32_bf16 v[126:129], v[130:133], v[162:165], v[126:129]
	v_mfma_f32_16x16x32_bf16 v[126:129], v[134:137], v[166:169], v[126:129]
	s_barrier
	s_setprio 1
	v_mfma_f32_16x16x32_bf16 v[122:125], v[142:145], v[166:169], v[122:125]
	v_mfma_f32_16x16x32_bf16 v[122:125], v[138:141], v[162:165], v[122:125]
	v_mfma_f32_16x16x32_bf16 v[106:109], v[138:141], v[182:185], v[106:109]
	v_mfma_f32_16x16x32_bf16 v[106:109], v[142:145], v[186:189], v[106:109]
	v_mfma_f32_16x16x32_bf16 v[110:113], v[134:137], v[186:189], v[110:113]
	v_mfma_f32_16x16x32_bf16 v[110:113], v[130:133], v[182:185], v[110:113]
	v_mfma_f32_16x16x32_bf16 v[94:97], v[130:133], v[190:193], v[94:97]
	v_mfma_f32_16x16x32_bf16 v[94:97], v[134:137], v[204:207], v[94:97]
	v_mfma_f32_16x16x32_bf16 v[90:93], v[142:145], v[204:207], v[90:93]
	v_mfma_f32_16x16x32_bf16 v[90:93], v[138:141], v[190:193], v[90:93]
	v_mfma_f32_16x16x32_bf16 v[74:77], v[138:141], v[208:211], v[74:77]
	v_mfma_f32_16x16x32_bf16 v[74:77], v[142:145], v[212:215], v[74:77]
	v_mfma_f32_16x16x32_bf16 v[78:81], v[134:137], v[212:215], v[78:81]
	v_mfma_f32_16x16x32_bf16 v[78:81], v[130:133], v[208:211], v[78:81]
	v_mfma_f32_16x16x32_bf16 v[118:121], v[146:149], v[162:165], v[118:121]
	v_mfma_f32_16x16x32_bf16 v[118:121], v[150:153], v[166:169], v[118:121]
	v_mfma_f32_16x16x32_bf16 v[114:117], v[158:161], v[166:169], v[114:117]
	v_mfma_f32_16x16x32_bf16 v[114:117], v[154:157], v[162:165], v[114:117]
	v_mfma_f32_16x16x32_bf16 v[98:101], v[154:157], v[182:185], v[98:101]
	v_mfma_f32_16x16x32_bf16 v[98:101], v[158:161], v[186:189], v[98:101]
	v_mfma_f32_16x16x32_bf16 v[102:105], v[150:153], v[186:189], v[102:105]
	v_mfma_f32_16x16x32_bf16 v[102:105], v[146:149], v[182:185], v[102:105]
	v_mfma_f32_16x16x32_bf16 v[86:89], v[146:149], v[190:193], v[86:89]
	v_mfma_f32_16x16x32_bf16 v[86:89], v[150:153], v[204:207], v[86:89]
	v_mfma_f32_16x16x32_bf16 v[82:85], v[158:161], v[204:207], v[82:85]
	v_mfma_f32_16x16x32_bf16 v[82:85], v[154:157], v[190:193], v[82:85]
	v_mfma_f32_16x16x32_bf16 v[66:69], v[154:157], v[208:211], v[66:69]
	v_mfma_f32_16x16x32_bf16 v[66:69], v[158:161], v[212:215], v[66:69]
	v_mfma_f32_16x16x32_bf16 v[70:73], v[150:153], v[212:215], v[70:73]
	v_mfma_f32_16x16x32_bf16 v[70:73], v[146:149], v[208:211], v[70:73]
	s_setprio 0
	s_barrier
	ds_read_b128 v[162:165], v227 offset:49152
	ds_read_b128 v[166:169], v227 offset:50176
	ds_read_b128 v[182:185], v227 offset:51200
	ds_read_b128 v[186:189], v227 offset:52224
	ds_read_b128 v[190:193], v227 offset:53248
	ds_read_b128 v[204:207], v227 offset:54272
	ds_read_b128 v[208:211], v227 offset:55296
	ds_read_b128 v[212:215], v227 offset:56320
	s_add_i32 s0, s73, s15
	s_add_u32 vcc_lo, s38, s94
	s_addc_u32 vcc_hi, s39, s95
	s_mov_b32 m0, s0
	s_nop 0
	global_load_lds_dwordx4 v172, vcc
	s_add_i32 m0, s0, 0x2000
	s_add_u32 s0, s38, 0x80080
	s_addc_u32 s1, s39, 0
	s_add_i32 s38, s75, s15
	global_load_lds_dwordx4 v176, vcc
	s_mov_b32 m0, s38
	s_nop 0
	global_load_lds_dwordx4 v172, s[0:1]
	s_add_i32 m0, s38, 0x2000
	s_nop 0
	global_load_lds_dwordx4 v176, s[0:1]
	s_waitcnt vmcnt(6)
	s_waitcnt lgkmcnt(0)
	v_mfma_f32_16x16x32_bf16 v[62:65], v[130:133], v[162:165], v[62:65]
	v_mfma_f32_16x16x32_bf16 v[62:65], v[134:137], v[166:169], v[62:65]
	s_barrier
	s_setprio 1
	v_mfma_f32_16x16x32_bf16 v[58:61], v[142:145], v[166:169], v[58:61]
	v_mfma_f32_16x16x32_bf16 v[58:61], v[138:141], v[162:165], v[58:61]
	v_mfma_f32_16x16x32_bf16 v[42:45], v[138:141], v[182:185], v[42:45]
	v_mfma_f32_16x16x32_bf16 v[42:45], v[142:145], v[186:189], v[42:45]
	v_mfma_f32_16x16x32_bf16 v[46:49], v[134:137], v[186:189], v[46:49]
	v_mfma_f32_16x16x32_bf16 v[46:49], v[130:133], v[182:185], v[46:49]
	v_mfma_f32_16x16x32_bf16 v[30:33], v[130:133], v[190:193], v[30:33]
	v_mfma_f32_16x16x32_bf16 v[30:33], v[134:137], v[204:207], v[30:33]
	v_mfma_f32_16x16x32_bf16 v[26:29], v[142:145], v[204:207], v[26:29]
	v_mfma_f32_16x16x32_bf16 v[26:29], v[138:141], v[190:193], v[26:29]
	v_mfma_f32_16x16x32_bf16 v[10:13], v[138:141], v[208:211], v[10:13]
	v_mfma_f32_16x16x32_bf16 v[10:13], v[142:145], v[212:215], v[10:13]
	s_add_u32 s51, s51, 0x100
	v_mfma_f32_16x16x32_bf16 v[14:17], v[134:137], v[212:215], v[14:17]
	v_mfma_f32_16x16x32_bf16 v[14:17], v[130:133], v[208:211], v[14:17]
	s_addc_u32 s70, s70, 0
	v_mfma_f32_16x16x32_bf16 v[54:57], v[146:149], v[162:165], v[54:57]
	v_mfma_f32_16x16x32_bf16 v[54:57], v[150:153], v[166:169], v[54:57]
	s_cmp_ge_i32 s71, s35
	v_mfma_f32_16x16x32_bf16 v[50:53], v[158:161], v[166:169], v[50:53]
	v_mfma_f32_16x16x32_bf16 v[50:53], v[154:157], v[162:165], v[50:53]
	s_mov_b64 s[0:1], s[4:5]
	v_mfma_f32_16x16x32_bf16 v[34:37], v[154:157], v[182:185], v[34:37]
	v_mfma_f32_16x16x32_bf16 v[34:37], v[158:161], v[186:189], v[34:37]
	s_mov_b32 s38, s71
	v_mfma_f32_16x16x32_bf16 v[38:41], v[150:153], v[186:189], v[38:41]
	v_mfma_f32_16x16x32_bf16 v[38:41], v[146:149], v[182:185], v[38:41]
	v_mfma_f32_16x16x32_bf16 v[22:25], v[146:149], v[190:193], v[22:25]
	v_mfma_f32_16x16x32_bf16 v[22:25], v[150:153], v[204:207], v[22:25]
	v_mfma_f32_16x16x32_bf16 v[18:21], v[158:161], v[204:207], v[18:21]
	v_mfma_f32_16x16x32_bf16 v[18:21], v[154:157], v[190:193], v[18:21]
	v_mfma_f32_16x16x32_bf16 v[2:5], v[154:157], v[208:211], v[2:5]
	v_mfma_f32_16x16x32_bf16 v[2:5], v[158:161], v[212:215], v[2:5]
	v_mfma_f32_16x16x32_bf16 v[6:9], v[150:153], v[212:215], v[6:9]
	v_mfma_f32_16x16x32_bf16 v[6:9], v[146:149], v[208:211], v[6:9]
	s_setprio 0
	s_barrier
	s_cbranch_scc0 .LBB0_305
	s_movk_i32 s51, 0x2000
	s_mov_b32 s73, 0x10000
	s_mov_b32 s75, 0x12000
	s_and_b64 vcc, exec, s[16:17]
	s_cbranch_vccz .LBB0_308

.LBB0_530:
	s_add_u32 vcc_lo, s14, 0xfff80000
	s_addc_u32 vcc_hi, s15, -1
	s_mov_b32 m0, s27
	s_nop 0
	global_load_lds_dwordx4 v138, vcc
	s_mov_b32 m0, s28
	s_nop 0
	global_load_lds_dwordx4 v140, vcc
	ds_read_b128 v[152:155], v145
	ds_read_b128 v[156:159], v145 offset:1024
	ds_read_b128 v[160:163], v145 offset:2048
	ds_read_b128 v[164:167], v145 offset:3072
	ds_read_b128 v[168:171], v145 offset:16384
	ds_read_b128 v[172:175], v145 offset:17408
	ds_read_b128 v[176:179], v145 offset:18432
	ds_read_b128 v[180:183], v145 offset:19456
	ds_read_b128 v[184:187], v151
	ds_read_b128 v[188:191], v151 offset:1024
	ds_read_b128 v[204:207], v151 offset:2048
	ds_read_b128 v[208:211], v151 offset:3072
	ds_read_b128 v[212:215], v151 offset:4096
	ds_read_b128 v[216:219], v151 offset:5120
	ds_read_b128 v[220:223], v151 offset:6144
	ds_read_b128 v[224:227], v151 offset:7168
	s_add_u32 s16, s14, 0xfff80080
	s_addc_u32 s17, s15, -1
	s_add_i32 s40, 0, 0x10000
	s_cmp_eq_u32 s39, 28
	s_cselect_b32 s19, s34, s17
	s_cselect_b32 s18, s35, s16
	s_cselect_b32 s17, s9, s38
	s_cselect_b32 s16, s36, s37
	s_add_i32 s42, 0, 0x14000
	s_add_i32 m0, s23, 0xc000
	s_nop 0
	global_load_lds_dwordx4 v138, s[14:15]
	s_add_i32 m0, s23, 0xe000
	s_nop 0
	global_load_lds_dwordx4 v140, s[14:15]
	s_waitcnt vmcnt(8)
	s_waitcnt lgkmcnt(0)
	v_mfma_f32_16x16x32_bf16 v[126:129], v[152:155], v[184:187], v[126:129]
	v_mfma_f32_16x16x32_bf16 v[126:129], v[156:159], v[188:191], v[126:129]
	s_barrier
	s_setprio 1
	v_mfma_f32_16x16x32_bf16 v[122:125], v[164:167], v[188:191], v[122:125]
	v_mfma_f32_16x16x32_bf16 v[122:125], v[160:163], v[184:187], v[122:125]
	v_mfma_f32_16x16x32_bf16 v[106:109], v[160:163], v[204:207], v[106:109]
	v_mfma_f32_16x16x32_bf16 v[106:109], v[164:167], v[208:211], v[106:109]
	v_mfma_f32_16x16x32_bf16 v[110:113], v[156:159], v[208:211], v[110:113]
	v_mfma_f32_16x16x32_bf16 v[110:113], v[152:155], v[204:207], v[110:113]
	v_mfma_f32_16x16x32_bf16 v[94:97], v[152:155], v[212:215], v[94:97]
	v_mfma_f32_16x16x32_bf16 v[94:97], v[156:159], v[216:219], v[94:97]
	v_mfma_f32_16x16x32_bf16 v[90:93], v[164:167], v[216:219], v[90:93]
	v_mfma_f32_16x16x32_bf16 v[90:93], v[160:163], v[212:215], v[90:93]
	v_mfma_f32_16x16x32_bf16 v[74:77], v[160:163], v[220:223], v[74:77]
	v_mfma_f32_16x16x32_bf16 v[74:77], v[164:167], v[224:227], v[74:77]
	v_mfma_f32_16x16x32_bf16 v[78:81], v[156:159], v[224:227], v[78:81]
	v_mfma_f32_16x16x32_bf16 v[78:81], v[152:155], v[220:223], v[78:81]
	v_mfma_f32_16x16x32_bf16 v[118:121], v[168:171], v[184:187], v[118:121]
	v_mfma_f32_16x16x32_bf16 v[118:121], v[172:175], v[188:191], v[118:121]
	v_mfma_f32_16x16x32_bf16 v[114:117], v[180:183], v[188:191], v[114:117]
	v_mfma_f32_16x16x32_bf16 v[114:117], v[176:179], v[184:187], v[114:117]
	v_mfma_f32_16x16x32_bf16 v[98:101], v[176:179], v[204:207], v[98:101]
	v_mfma_f32_16x16x32_bf16 v[98:101], v[180:183], v[208:211], v[98:101]
	v_mfma_f32_16x16x32_bf16 v[102:105], v[172:175], v[208:211], v[102:105]
	v_mfma_f32_16x16x32_bf16 v[102:105], v[168:171], v[204:207], v[102:105]
	v_mfma_f32_16x16x32_bf16 v[86:89], v[168:171], v[212:215], v[86:89]
	v_mfma_f32_16x16x32_bf16 v[86:89], v[172:175], v[216:219], v[86:89]
	v_mfma_f32_16x16x32_bf16 v[82:85], v[180:183], v[216:219], v[82:85]
	v_mfma_f32_16x16x32_bf16 v[82:85], v[176:179], v[212:215], v[82:85]
	v_mfma_f32_16x16x32_bf16 v[66:69], v[176:179], v[220:223], v[66:69]
	v_mfma_f32_16x16x32_bf16 v[66:69], v[180:183], v[224:227], v[66:69]
	v_mfma_f32_16x16x32_bf16 v[70:73], v[172:175], v[224:227], v[70:73]
	v_mfma_f32_16x16x32_bf16 v[70:73], v[168:171], v[220:223], v[70:73]
	s_setprio 0
	s_barrier
	ds_read_b128 v[184:187], v151 offset:16384
	ds_read_b128 v[188:191], v151 offset:17408
	ds_read_b128 v[204:207], v151 offset:18432
	ds_read_b128 v[208:211], v151 offset:19456
	ds_read_b128 v[212:215], v151 offset:20480
	ds_read_b128 v[216:219], v151 offset:21504
	ds_read_b128 v[220:223], v151 offset:22528
	ds_read_b128 v[224:227], v151 offset:23552
	s_add_i32 s40, s40, s22
	s_mov_b32 m0, s40
	s_nop 0
	global_load_lds_dwordx4 v134, s[16:17]
	s_add_i32 m0, s40, 0x2000
	s_add_u32 s40, s16, 0x80000
	s_addc_u32 s41, s17, 0
	s_add_i32 s42, s42, s22
	global_load_lds_dwordx4 v130, s[16:17]
	s_mov_b32 m0, s42
	s_nop 0
	global_load_lds_dwordx4 v134, s[40:41]
	s_add_i32 m0, s42, 0x2000
	s_nop 0
	global_load_lds_dwordx4 v130, s[40:41]
	s_waitcnt vmcnt(6)
	s_waitcnt lgkmcnt(0)
	v_mfma_f32_16x16x32_bf16 v[62:65], v[152:155], v[184:187], v[62:65]
	v_mfma_f32_16x16x32_bf16 v[62:65], v[156:159], v[188:191], v[62:65]
	s_barrier
	s_setprio 1
	v_mfma_f32_16x16x32_bf16 v[58:61], v[164:167], v[188:191], v[58:61]
	v_mfma_f32_16x16x32_bf16 v[58:61], v[160:163], v[184:187], v[58:61]
	v_mfma_f32_16x16x32_bf16 v[42:45], v[160:163], v[204:207], v[42:45]
	v_mfma_f32_16x16x32_bf16 v[42:45], v[164:167], v[208:211], v[42:45]
	v_mfma_f32_16x16x32_bf16 v[46:49], v[156:159], v[208:211], v[46:49]
	v_mfma_f32_16x16x32_bf16 v[46:49], v[152:155], v[204:207], v[46:49]
	v_mfma_f32_16x16x32_bf16 v[30:33], v[152:155], v[212:215], v[30:33]
	v_mfma_f32_16x16x32_bf16 v[30:33], v[156:159], v[216:219], v[30:33]
	v_mfma_f32_16x16x32_bf16 v[26:29], v[164:167], v[216:219], v[26:29]
	v_mfma_f32_16x16x32_bf16 v[26:29], v[160:163], v[212:215], v[26:29]
	v_mfma_f32_16x16x32_bf16 v[10:13], v[160:163], v[220:223], v[10:13]
	v_mfma_f32_16x16x32_bf16 v[10:13], v[164:167], v[224:227], v[10:13]
	v_mfma_f32_16x16x32_bf16 v[14:17], v[156:159], v[224:227], v[14:17]
	v_mfma_f32_16x16x32_bf16 v[14:17], v[152:155], v[220:223], v[14:17]
	v_mfma_f32_16x16x32_bf16 v[54:57], v[168:171], v[184:187], v[54:57]
	v_mfma_f32_16x16x32_bf16 v[54:57], v[172:175], v[188:191], v[54:57]
	v_mfma_f32_16x16x32_bf16 v[50:53], v[180:183], v[188:191], v[50:53]
	v_mfma_f32_16x16x32_bf16 v[50:53], v[176:179], v[184:187], v[50:53]
	v_mfma_f32_16x16x32_bf16 v[34:37], v[176:179], v[204:207], v[34:37]
	v_mfma_f32_16x16x32_bf16 v[34:37], v[180:183], v[208:211], v[34:37]
	v_mfma_f32_16x16x32_bf16 v[38:41], v[172:175], v[208:211], v[38:41]
	v_mfma_f32_16x16x32_bf16 v[38:41], v[168:171], v[204:207], v[38:41]
	v_mfma_f32_16x16x32_bf16 v[22:25], v[168:171], v[212:215], v[22:25]
	v_mfma_f32_16x16x32_bf16 v[22:25], v[172:175], v[216:219], v[22:25]
	v_mfma_f32_16x16x32_bf16 v[18:21], v[180:183], v[216:219], v[18:21]
	v_mfma_f32_16x16x32_bf16 v[18:21], v[176:179], v[212:215], v[18:21]
	v_mfma_f32_16x16x32_bf16 v[2:5], v[176:179], v[220:223], v[2:5]
	v_mfma_f32_16x16x32_bf16 v[2:5], v[180:183], v[224:227], v[2:5]
	v_mfma_f32_16x16x32_bf16 v[6:9], v[172:175], v[224:227], v[6:9]
	v_mfma_f32_16x16x32_bf16 v[6:9], v[168:171], v[220:223], v[6:9]
	s_setprio 0
	s_barrier
	s_mov_b32 m0, s23
	s_nop 0
	global_load_lds_dwordx4 v136, s[18:19]
	s_mov_b32 m0, s24
	s_nop 0
	global_load_lds_dwordx4 v132, s[18:19]
	ds_read_b128 v[152:155], v145 offset:32768
	ds_read_b128 v[156:159], v145 offset:33792
	ds_read_b128 v[160:163], v145 offset:34816
	ds_read_b128 v[164:167], v145 offset:35840
	ds_read_b128 v[168:171], v145 offset:49152
	ds_read_b128 v[172:175], v145 offset:50176
	ds_read_b128 v[176:179], v145 offset:51200
	ds_read_b128 v[180:183], v145 offset:52224
	ds_read_b128 v[184:187], v151 offset:32768
	ds_read_b128 v[188:191], v151 offset:33792
	ds_read_b128 v[204:207], v151 offset:34816
	ds_read_b128 v[208:211], v151 offset:35840
	ds_read_b128 v[212:215], v151 offset:36864
	ds_read_b128 v[216:219], v151 offset:37888
	ds_read_b128 v[220:223], v151 offset:38912
	ds_read_b128 v[224:227], v151 offset:39936
	s_add_i32 s40, 0, 0x18000
	s_add_i32 s41, 0, 0x1c000
	s_add_u32 s18, s18, 0x80000
	s_addc_u32 s19, s19, 0
	s_mov_b32 m0, s25
	s_nop 0
	global_load_lds_dwordx4 v136, s[18:19]
	s_mov_b32 m0, s26
	s_nop 0
	global_load_lds_dwordx4 v132, s[18:19]
	s_waitcnt vmcnt(8)
	s_waitcnt lgkmcnt(0)
	v_mfma_f32_16x16x32_bf16 v[126:129], v[152:155], v[184:187], v[126:129]
	v_mfma_f32_16x16x32_bf16 v[126:129], v[156:159], v[188:191], v[126:129]
	s_barrier
	s_setprio 1
	v_mfma_f32_16x16x32_bf16 v[122:125], v[164:167], v[188:191], v[122:125]
	v_mfma_f32_16x16x32_bf16 v[122:125], v[160:163], v[184:187], v[122:125]
	v_mfma_f32_16x16x32_bf16 v[106:109], v[160:163], v[204:207], v[106:109]
	v_mfma_f32_16x16x32_bf16 v[106:109], v[164:167], v[208:211], v[106:109]
	v_mfma_f32_16x16x32_bf16 v[110:113], v[156:159], v[208:211], v[110:113]
	v_mfma_f32_16x16x32_bf16 v[110:113], v[152:155], v[204:207], v[110:113]
	v_mfma_f32_16x16x32_bf16 v[94:97], v[152:155], v[212:215], v[94:97]
	v_mfma_f32_16x16x32_bf16 v[94:97], v[156:159], v[216:219], v[94:97]
	v_mfma_f32_16x16x32_bf16 v[90:93], v[164:167], v[216:219], v[90:93]
	v_mfma_f32_16x16x32_bf16 v[90:93], v[160:163], v[212:215], v[90:93]
	v_mfma_f32_16x16x32_bf16 v[74:77], v[160:163], v[220:223], v[74:77]
	v_mfma_f32_16x16x32_bf16 v[74:77], v[164:167], v[224:227], v[74:77]
	v_mfma_f32_16x16x32_bf16 v[78:81], v[156:159], v[224:227], v[78:81]
	v_mfma_f32_16x16x32_bf16 v[78:81], v[152:155], v[220:223], v[78:81]
	v_mfma_f32_16x16x32_bf16 v[118:121], v[168:171], v[184:187], v[118:121]
	v_mfma_f32_16x16x32_bf16 v[118:121], v[172:175], v[188:191], v[118:121]
	v_mfma_f32_16x16x32_bf16 v[114:117], v[180:183], v[188:191], v[114:117]
	v_mfma_f32_16x16x32_bf16 v[114:117], v[176:179], v[184:187], v[114:117]
	v_mfma_f32_16x16x32_bf16 v[98:101], v[176:179], v[204:207], v[98:101]
	v_mfma_f32_16x16x32_bf16 v[98:101], v[180:183], v[208:211], v[98:101]
	v_mfma_f32_16x16x32_bf16 v[102:105], v[172:175], v[208:211], v[102:105]
	v_mfma_f32_16x16x32_bf16 v[102:105], v[168:171], v[204:207], v[102:105]
	v_mfma_f32_16x16x32_bf16 v[86:89], v[168:171], v[212:215], v[86:89]
	v_mfma_f32_16x16x32_bf16 v[86:89], v[172:175], v[216:219], v[86:89]
	v_mfma_f32_16x16x32_bf16 v[82:85], v[180:183], v[216:219], v[82:85]
	v_mfma_f32_16x16x32_bf16 v[82:85], v[176:179], v[212:215], v[82:85]
	v_mfma_f32_16x16x32_bf16 v[66:69], v[176:179], v[220:223], v[66:69]
	v_mfma_f32_16x16x32_bf16 v[66:69], v[180:183], v[224:227], v[66:69]
	v_mfma_f32_16x16x32_bf16 v[70:73], v[172:175], v[224:227], v[70:73]
	v_mfma_f32_16x16x32_bf16 v[70:73], v[168:171], v[220:223], v[70:73]
	s_setprio 0
	s_barrier
	ds_read_b128 v[184:187], v151 offset:49152
	ds_read_b128 v[188:191], v151 offset:50176
	ds_read_b128 v[204:207], v151 offset:51200
	ds_read_b128 v[208:211], v151 offset:52224
	ds_read_b128 v[212:215], v151 offset:53248
	ds_read_b128 v[216:219], v151 offset:54272
	ds_read_b128 v[220:223], v151 offset:55296
	ds_read_b128 v[224:227], v151 offset:56320
	s_add_i32 s18, s40, s22
	s_add_u32 vcc_lo, s16, s94
	s_addc_u32 vcc_hi, s17, s95
	s_mov_b32 m0, s18
	s_nop 0
	global_load_lds_dwordx4 v134, vcc
	s_add_i32 m0, s18, 0x2000
	s_add_u32 s16, s16, 0x80080
	s_addc_u32 s17, s17, 0
	s_add_i32 s18, s41, s22
	global_load_lds_dwordx4 v130, vcc
	s_mov_b32 m0, s18
	s_nop 0
	global_load_lds_dwordx4 v134, s[16:17]
	s_add_i32 m0, s18, 0x2000
	s_nop 0
	global_load_lds_dwordx4 v130, s[16:17]
	s_waitcnt vmcnt(6)
	s_waitcnt lgkmcnt(0)
	v_mfma_f32_16x16x32_bf16 v[62:65], v[152:155], v[184:187], v[62:65]
	v_mfma_f32_16x16x32_bf16 v[62:65], v[156:159], v[188:191], v[62:65]
	s_barrier
	s_setprio 1
	v_mfma_f32_16x16x32_bf16 v[58:61], v[164:167], v[188:191], v[58:61]
	v_mfma_f32_16x16x32_bf16 v[58:61], v[160:163], v[184:187], v[58:61]
	v_mfma_f32_16x16x32_bf16 v[42:45], v[160:163], v[204:207], v[42:45]
	v_mfma_f32_16x16x32_bf16 v[42:45], v[164:167], v[208:211], v[42:45]
	v_mfma_f32_16x16x32_bf16 v[46:49], v[156:159], v[208:211], v[46:49]
	v_mfma_f32_16x16x32_bf16 v[46:49], v[152:155], v[204:207], v[46:49]
	v_mfma_f32_16x16x32_bf16 v[30:33], v[152:155], v[212:215], v[30:33]
	v_mfma_f32_16x16x32_bf16 v[30:33], v[156:159], v[216:219], v[30:33]
	v_mfma_f32_16x16x32_bf16 v[26:29], v[164:167], v[216:219], v[26:29]
	v_mfma_f32_16x16x32_bf16 v[26:29], v[160:163], v[212:215], v[26:29]
	v_mfma_f32_16x16x32_bf16 v[10:13], v[160:163], v[220:223], v[10:13]
	v_mfma_f32_16x16x32_bf16 v[10:13], v[164:167], v[224:227], v[10:13]
	s_add_i32 s39, s39, 2
	v_mfma_f32_16x16x32_bf16 v[14:17], v[156:159], v[224:227], v[14:17]
	v_mfma_f32_16x16x32_bf16 v[14:17], v[152:155], v[220:223], v[14:17]
	s_add_u32 s14, s14, 0x100
	v_mfma_f32_16x16x32_bf16 v[54:57], v[168:171], v[184:187], v[54:57]
	v_mfma_f32_16x16x32_bf16 v[54:57], v[172:175], v[188:191], v[54:57]
	s_addc_u32 s15, s15, 0
	v_mfma_f32_16x16x32_bf16 v[50:53], v[180:183], v[188:191], v[50:53]
	v_mfma_f32_16x16x32_bf16 v[50:53], v[176:179], v[184:187], v[50:53]
	s_add_u32 s37, s37, 0x100
	v_mfma_f32_16x16x32_bf16 v[34:37], v[176:179], v[204:207], v[34:37]
	v_mfma_f32_16x16x32_bf16 v[34:37], v[180:183], v[208:211], v[34:37]
	s_addc_u32 s38, s38, 0
	v_mfma_f32_16x16x32_bf16 v[38:41], v[172:175], v[208:211], v[38:41]
	v_mfma_f32_16x16x32_bf16 v[38:41], v[168:171], v[204:207], v[38:41]
	s_cmp_gt_u32 s39, 29
	v_mfma_f32_16x16x32_bf16 v[22:25], v[168:171], v[212:215], v[22:25]
	v_mfma_f32_16x16x32_bf16 v[22:25], v[172:175], v[216:219], v[22:25]
	v_mfma_f32_16x16x32_bf16 v[18:21], v[180:183], v[216:219], v[18:21]
	v_mfma_f32_16x16x32_bf16 v[18:21], v[176:179], v[212:215], v[18:21]
	v_mfma_f32_16x16x32_bf16 v[2:5], v[176:179], v[220:223], v[2:5]
	v_mfma_f32_16x16x32_bf16 v[2:5], v[180:183], v[224:227], v[2:5]
	v_mfma_f32_16x16x32_bf16 v[6:9], v[172:175], v[224:227], v[6:9]
	v_mfma_f32_16x16x32_bf16 v[6:9], v[168:171], v[220:223], v[6:9]
	s_setprio 0
	s_barrier
	s_cbranch_scc0 .LBB0_530
	s_and_b64 vcc, exec, s[6:7]
	s_cbranch_vccz .LBB0_533
	s_barrier

.LBB0_758:
	s_add_i32 m0, s33, 0x18000
	v_lshl_add_u64 v[4:5], v[4:5], 0, s[94:95]
	s_waitcnt vmcnt(2)
	s_barrier
	global_load_lds_dwordx4 v[4:5], off
	v_lshl_add_u64 v[4:5], v[6:7], 0, s[94:95]
	s_add_i32 m0, s33, 0x1a000
	s_add_i32 s37, s33, 0x8000
	global_load_lds_dwordx4 v[4:5], off
	v_lshl_add_u64 v[4:5], v[12:13], 0, s[94:95]
	s_mov_b32 m0, s37
	s_add_i32 s38, s33, 0xa000
	global_load_lds_dwordx4 v[4:5], off
	v_lshl_add_u64 v[4:5], v[14:15], 0, s[94:95]
	s_mov_b32 m0, s38
	v_bfe_u32 v6, v16, 4, 2
	global_load_lds_dwordx4 v[4:5], off
	s_add_i32 m0, s33, 0x1c000
	v_lshl_add_u64 v[4:5], v[8:9], 0, s[94:95]
	global_load_lds_dwordx4 v[4:5], off
	v_lshl_add_u64 v[4:5], v[10:11], 0, s[94:95]
	s_add_i32 m0, s33, 0x1e000
	v_and_b32_e32 v7, 15, v16
	global_load_lds_dwordx4 v[4:5], off
	v_lshlrev_b32_e32 v8, 4, v6
	v_lshlrev_b32_e32 v9, 2, v16
	s_lshl_b32 s1, s1, 5
	v_lshl_or_b32 v8, v7, 6, v8
	s_lshl_b32 s3, s0, 13
	v_and_b32_e32 v9, 32, v9
	s_and_b32 s1, s1, 0x60
	v_bitop3_b32 v10, v8, s3, v9 bitop3:0xde
	s_lshl_b32 s3, s1, 7
	v_bitop3_b32 v231, v8, s3, v9 bitop3:0xde
	v_add_u32_e32 v231, 0x10000, v231
	s_add_i32 s3, s53, -1
	v_lshl_or_b32 v223, s0, 6, v7
	s_lshl_b32 s0, s0, 11
	s_lshr_b32 s3, s3, 1
	s_and_b32 s3, s3, 0x7ffffffc
	s_add_i32 s0, s0, 0
	s_add_i32 s4, s0, s3
	s_cmpk_lt_u32 s2, 0x100
	v_cmp_eq_u32_e64 s[2:3], 0, v6
	v_lshl_or_b32 v239, v6, 3, s1
	v_add_u32_e32 v6, v19, v17
	s_waitcnt vmcnt(6)
	v_add_lshl_u32 v194, v6, v18, 1
	v_add_u32_e32 v6, v22, v20
	v_lshlrev_b32_e32 v7, 5, v7
	s_cselect_b64 s[14:15], -1, 0
	s_add_i32 s4, s4, 0x20000
	s_add_i32 s0, s0, 0x1fffd
	v_lshl_add_u64 v[212:213], s[12:13], 0, v[194:195]
	v_add_lshl_u32 v194, v6, v21, 1
	v_mov_b32_e32 v3, v2
	v_mov_b32_e32 v4, v2
	v_mov_b32_e32 v5, v2
	s_mov_b32 s39, 0
	s_mov_b32 s11, s85
	v_add_u32_e32 v198, s4, v7
	v_add_u32_e32 v199, s0, v7
	v_lshl_add_u64 v[214:215], s[12:13], 0, v[194:195]
	v_add_u32_e32 v197, 0, v10
	s_mov_b32 s21, 0
	s_barrier
	s_branch .LBB0_761

.LBB0_769:
	s_sub_u32 vcc_lo, s22, s12
	s_subb_u32 vcc_hi, s23, 0
	s_mov_b32 m0, s37
	s_nop 0
	global_load_lds_dwordx4 v214, vcc
	s_mov_b32 m0, s38
	s_nop 0
	global_load_lds_dwordx4 v212, vcc
	ds_read_b128 v[132:135], v231
	ds_read_b128 v[136:139], v231 offset:1024
	ds_read_b128 v[140:143], v231 offset:2048
	ds_read_b128 v[144:147], v231 offset:3072
	ds_read_b128 v[148:151], v231 offset:16384
	ds_read_b128 v[152:155], v231 offset:17408
	ds_read_b128 v[156:159], v231 offset:18432
	ds_read_b128 v[160:163], v231 offset:19456
	ds_read_b128 v[164:167], v197
	ds_read_b128 v[168:171], v197 offset:1024
	ds_read_b128 v[172:175], v197 offset:2048
	ds_read_b128 v[176:179], v197 offset:3072
	ds_read_b128 v[180:183], v197 offset:4096
	ds_read_b128 v[184:187], v197 offset:5120
	ds_read_b128 v[188:191], v197 offset:6144
	ds_read_b128 v[216:219], v197 offset:7168
	s_add_u32 s24, s22, 0x80
	s_addc_u32 s25, s23, 0
	s_add_i32 s57, 0, 0x10000
	s_cmp_eq_u32 s53, s56
	s_cselect_b32 s25, s1, s25
	s_cselect_b32 s24, s0, s24
	s_cselect_b32 s59, s19, s55
	s_cselect_b32 s58, s18, s54
	s_add_i32 s60, 0, 0x14000
	s_add_i32 m0, s33, 0xc000
	s_nop 0
	global_load_lds_dwordx4 v214, s[22:23]
	s_add_i32 m0, s33, 0xe000
	s_nop 0
	global_load_lds_dwordx4 v212, s[22:23]
	s_waitcnt vmcnt(8)
	s_waitcnt lgkmcnt(0)
	v_mfma_f32_16x16x32_bf16 v[126:129], v[132:135], v[164:167], v[126:129]
	v_mfma_f32_16x16x32_bf16 v[126:129], v[136:139], v[168:171], v[126:129]
	s_barrier
	s_setprio 1
	v_mfma_f32_16x16x32_bf16 v[122:125], v[144:147], v[168:171], v[122:125]
	v_mfma_f32_16x16x32_bf16 v[122:125], v[140:143], v[164:167], v[122:125]
	v_mfma_f32_16x16x32_bf16 v[106:109], v[140:143], v[172:175], v[106:109]
	v_mfma_f32_16x16x32_bf16 v[106:109], v[144:147], v[176:179], v[106:109]
	v_mfma_f32_16x16x32_bf16 v[110:113], v[136:139], v[176:179], v[110:113]
	v_mfma_f32_16x16x32_bf16 v[110:113], v[132:135], v[172:175], v[110:113]
	v_mfma_f32_16x16x32_bf16 v[94:97], v[132:135], v[180:183], v[94:97]
	v_mfma_f32_16x16x32_bf16 v[94:97], v[136:139], v[184:187], v[94:97]
	v_mfma_f32_16x16x32_bf16 v[90:93], v[144:147], v[184:187], v[90:93]
	v_mfma_f32_16x16x32_bf16 v[90:93], v[140:143], v[180:183], v[90:93]
	v_mfma_f32_16x16x32_bf16 v[74:77], v[140:143], v[188:191], v[74:77]
	v_mfma_f32_16x16x32_bf16 v[74:77], v[144:147], v[216:219], v[74:77]
	v_mfma_f32_16x16x32_bf16 v[78:81], v[136:139], v[216:219], v[78:81]
	v_mfma_f32_16x16x32_bf16 v[78:81], v[132:135], v[188:191], v[78:81]
	v_mfma_f32_16x16x32_bf16 v[118:121], v[148:151], v[164:167], v[118:121]
	v_mfma_f32_16x16x32_bf16 v[118:121], v[152:155], v[168:171], v[118:121]
	v_mfma_f32_16x16x32_bf16 v[114:117], v[160:163], v[168:171], v[114:117]
	v_mfma_f32_16x16x32_bf16 v[114:117], v[156:159], v[164:167], v[114:117]
	v_mfma_f32_16x16x32_bf16 v[98:101], v[156:159], v[172:175], v[98:101]
	v_mfma_f32_16x16x32_bf16 v[98:101], v[160:163], v[176:179], v[98:101]
	v_mfma_f32_16x16x32_bf16 v[102:105], v[152:155], v[176:179], v[102:105]
	v_mfma_f32_16x16x32_bf16 v[102:105], v[148:151], v[172:175], v[102:105]
	v_mfma_f32_16x16x32_bf16 v[86:89], v[148:151], v[180:183], v[86:89]
	v_mfma_f32_16x16x32_bf16 v[86:89], v[152:155], v[184:187], v[86:89]
	v_mfma_f32_16x16x32_bf16 v[82:85], v[160:163], v[184:187], v[82:85]
	v_mfma_f32_16x16x32_bf16 v[82:85], v[156:159], v[180:183], v[82:85]
	v_mfma_f32_16x16x32_bf16 v[66:69], v[156:159], v[188:191], v[66:69]
	v_mfma_f32_16x16x32_bf16 v[66:69], v[160:163], v[216:219], v[66:69]
	v_mfma_f32_16x16x32_bf16 v[70:73], v[152:155], v[216:219], v[70:73]
	v_mfma_f32_16x16x32_bf16 v[70:73], v[148:151], v[188:191], v[70:73]
	s_setprio 0
	s_barrier
	ds_read_b128 v[164:167], v197 offset:16384
	ds_read_b128 v[168:171], v197 offset:17408
	ds_read_b128 v[172:175], v197 offset:18432
	ds_read_b128 v[176:179], v197 offset:19456
	ds_read_b128 v[180:183], v197 offset:20480
	ds_read_b128 v[184:187], v197 offset:21504
	ds_read_b128 v[188:191], v197 offset:22528
	ds_read_b128 v[216:219], v197 offset:23552
	s_add_i32 s57, s57, s26
	v_lshl_add_u64 v[192:193], s[58:59], 0, v[208:209]
	s_mov_b32 m0, s57
	s_nop 0
	global_load_lds_dwordx4 v208, s[58:59]
	s_add_i32 m0, s57, 0x2000
	v_lshl_add_u64 v[220:221], s[58:59], 0, v[204:205]
	s_add_u32 s58, s58, s12
	s_addc_u32 s59, s59, 0
	s_add_i32 s57, s60, s26
	global_load_lds_dwordx4 v[220:221], off
	v_lshl_add_u64 v[224:225], s[58:59], 0, v[208:209]
	s_mov_b32 m0, s57
	v_lshl_add_u64 v[226:227], s[58:59], 0, v[204:205]
	global_load_lds_dwordx4 v208, s[58:59]
	s_add_i32 m0, s57, 0x2000
	s_nop 0
	global_load_lds_dwordx4 v204, s[58:59]
	s_waitcnt vmcnt(6)
	s_waitcnt lgkmcnt(0)
	v_mfma_f32_16x16x32_bf16 v[62:65], v[132:135], v[164:167], v[62:65]
	v_mfma_f32_16x16x32_bf16 v[62:65], v[136:139], v[168:171], v[62:65]
	s_barrier
	s_setprio 1
	v_mfma_f32_16x16x32_bf16 v[58:61], v[144:147], v[168:171], v[58:61]
	v_mfma_f32_16x16x32_bf16 v[58:61], v[140:143], v[164:167], v[58:61]
	v_mfma_f32_16x16x32_bf16 v[42:45], v[140:143], v[172:175], v[42:45]
	v_mfma_f32_16x16x32_bf16 v[42:45], v[144:147], v[176:179], v[42:45]
	v_mfma_f32_16x16x32_bf16 v[46:49], v[136:139], v[176:179], v[46:49]
	v_mfma_f32_16x16x32_bf16 v[46:49], v[132:135], v[172:175], v[46:49]
	v_mfma_f32_16x16x32_bf16 v[30:33], v[132:135], v[180:183], v[30:33]
	v_mfma_f32_16x16x32_bf16 v[30:33], v[136:139], v[184:187], v[30:33]
	v_mfma_f32_16x16x32_bf16 v[26:29], v[144:147], v[184:187], v[26:29]
	v_mfma_f32_16x16x32_bf16 v[26:29], v[140:143], v[180:183], v[26:29]
	v_mfma_f32_16x16x32_bf16 v[10:13], v[140:143], v[188:191], v[10:13]
	v_mfma_f32_16x16x32_bf16 v[10:13], v[144:147], v[216:219], v[10:13]
	v_mfma_f32_16x16x32_bf16 v[14:17], v[136:139], v[216:219], v[14:17]
	v_mfma_f32_16x16x32_bf16 v[14:17], v[132:135], v[188:191], v[14:17]
	v_mfma_f32_16x16x32_bf16 v[54:57], v[148:151], v[164:167], v[54:57]
	v_mfma_f32_16x16x32_bf16 v[54:57], v[152:155], v[168:171], v[54:57]
	v_mfma_f32_16x16x32_bf16 v[50:53], v[160:163], v[168:171], v[50:53]
	v_mfma_f32_16x16x32_bf16 v[50:53], v[156:159], v[164:167], v[50:53]
	v_mfma_f32_16x16x32_bf16 v[34:37], v[156:159], v[172:175], v[34:37]
	v_mfma_f32_16x16x32_bf16 v[34:37], v[160:163], v[176:179], v[34:37]
	v_mfma_f32_16x16x32_bf16 v[38:41], v[152:155], v[176:179], v[38:41]
	v_mfma_f32_16x16x32_bf16 v[38:41], v[148:151], v[172:175], v[38:41]
	v_mfma_f32_16x16x32_bf16 v[22:25], v[148:151], v[180:183], v[22:25]
	v_mfma_f32_16x16x32_bf16 v[22:25], v[152:155], v[184:187], v[22:25]
	v_mfma_f32_16x16x32_bf16 v[18:21], v[160:163], v[184:187], v[18:21]
	v_mfma_f32_16x16x32_bf16 v[18:21], v[156:159], v[180:183], v[18:21]
	v_mfma_f32_16x16x32_bf16 v[2:5], v[156:159], v[188:191], v[2:5]
	v_mfma_f32_16x16x32_bf16 v[2:5], v[160:163], v[216:219], v[2:5]
	v_mfma_f32_16x16x32_bf16 v[6:9], v[152:155], v[216:219], v[6:9]
	v_mfma_f32_16x16x32_bf16 v[6:9], v[148:151], v[188:191], v[6:9]
	s_setprio 0
	s_barrier
	s_mov_b32 m0, s33
	s_nop 0
	global_load_lds_dwordx4 v210, s[24:25]
	s_mov_b32 m0, s34
	s_nop 0
	global_load_lds_dwordx4 v206, s[24:25]
	ds_read_b128 v[132:135], v231 offset:32768
	ds_read_b128 v[136:139], v231 offset:33792
	ds_read_b128 v[140:143], v231 offset:34816
	ds_read_b128 v[144:147], v231 offset:35840
	ds_read_b128 v[148:151], v231 offset:49152
	ds_read_b128 v[152:155], v231 offset:50176
	ds_read_b128 v[156:159], v231 offset:51200
	ds_read_b128 v[160:163], v231 offset:52224
	ds_read_b128 v[164:167], v197 offset:32768
	ds_read_b128 v[168:171], v197 offset:33792
	ds_read_b128 v[172:175], v197 offset:34816
	ds_read_b128 v[176:179], v197 offset:35840
	ds_read_b128 v[180:183], v197 offset:36864
	ds_read_b128 v[184:187], v197 offset:37888
	ds_read_b128 v[188:191], v197 offset:38912
	ds_read_b128 v[216:219], v197 offset:39936
	s_add_i32 s57, 0, 0x18000
	s_add_i32 s58, 0, 0x1c000
	s_add_u32 s24, s24, s12
	s_addc_u32 s25, s25, 0
	s_mov_b32 m0, s35
	s_nop 0
	global_load_lds_dwordx4 v210, s[24:25]
	s_mov_b32 m0, s36
	s_nop 0
	global_load_lds_dwordx4 v206, s[24:25]
	s_waitcnt vmcnt(8)
	s_waitcnt lgkmcnt(0)
	v_mfma_f32_16x16x32_bf16 v[126:129], v[132:135], v[164:167], v[126:129]
	v_mfma_f32_16x16x32_bf16 v[126:129], v[136:139], v[168:171], v[126:129]
	s_barrier
	s_setprio 1
	v_mfma_f32_16x16x32_bf16 v[122:125], v[144:147], v[168:171], v[122:125]
	v_mfma_f32_16x16x32_bf16 v[122:125], v[140:143], v[164:167], v[122:125]
	v_mfma_f32_16x16x32_bf16 v[106:109], v[140:143], v[172:175], v[106:109]
	v_mfma_f32_16x16x32_bf16 v[106:109], v[144:147], v[176:179], v[106:109]
	v_mfma_f32_16x16x32_bf16 v[110:113], v[136:139], v[176:179], v[110:113]
	v_mfma_f32_16x16x32_bf16 v[110:113], v[132:135], v[172:175], v[110:113]
	v_mfma_f32_16x16x32_bf16 v[94:97], v[132:135], v[180:183], v[94:97]
	v_mfma_f32_16x16x32_bf16 v[94:97], v[136:139], v[184:187], v[94:97]
	v_mfma_f32_16x16x32_bf16 v[90:93], v[144:147], v[184:187], v[90:93]
	v_mfma_f32_16x16x32_bf16 v[90:93], v[140:143], v[180:183], v[90:93]
	v_mfma_f32_16x16x32_bf16 v[74:77], v[140:143], v[188:191], v[74:77]
	v_mfma_f32_16x16x32_bf16 v[74:77], v[144:147], v[216:219], v[74:77]
	v_mfma_f32_16x16x32_bf16 v[78:81], v[136:139], v[216:219], v[78:81]
	v_mfma_f32_16x16x32_bf16 v[78:81], v[132:135], v[188:191], v[78:81]
	v_mfma_f32_16x16x32_bf16 v[118:121], v[148:151], v[164:167], v[118:121]
	v_mfma_f32_16x16x32_bf16 v[118:121], v[152:155], v[168:171], v[118:121]
	v_mfma_f32_16x16x32_bf16 v[114:117], v[160:163], v[168:171], v[114:117]
	v_mfma_f32_16x16x32_bf16 v[114:117], v[156:159], v[164:167], v[114:117]
	v_mfma_f32_16x16x32_bf16 v[98:101], v[156:159], v[172:175], v[98:101]
	v_mfma_f32_16x16x32_bf16 v[98:101], v[160:163], v[176:179], v[98:101]
	v_mfma_f32_16x16x32_bf16 v[102:105], v[152:155], v[176:179], v[102:105]
	v_mfma_f32_16x16x32_bf16 v[102:105], v[148:151], v[172:175], v[102:105]
	v_mfma_f32_16x16x32_bf16 v[86:89], v[148:151], v[180:183], v[86:89]
	v_mfma_f32_16x16x32_bf16 v[86:89], v[152:155], v[184:187], v[86:89]
	v_mfma_f32_16x16x32_bf16 v[82:85], v[160:163], v[184:187], v[82:85]
	v_mfma_f32_16x16x32_bf16 v[82:85], v[156:159], v[180:183], v[82:85]
	v_mfma_f32_16x16x32_bf16 v[66:69], v[156:159], v[188:191], v[66:69]
	v_mfma_f32_16x16x32_bf16 v[66:69], v[160:163], v[216:219], v[66:69]
	v_mfma_f32_16x16x32_bf16 v[70:73], v[152:155], v[216:219], v[70:73]
	v_mfma_f32_16x16x32_bf16 v[70:73], v[148:151], v[188:191], v[70:73]
	s_setprio 0
	s_barrier
	ds_read_b128 v[164:167], v197 offset:49152
	ds_read_b128 v[168:171], v197 offset:50176
	ds_read_b128 v[172:175], v197 offset:51200
	ds_read_b128 v[176:179], v197 offset:52224
	ds_read_b128 v[180:183], v197 offset:53248
	ds_read_b128 v[184:187], v197 offset:54272
	ds_read_b128 v[188:191], v197 offset:55296
	ds_read_b128 v[216:219], v197 offset:56320
	s_add_i32 s24, s57, s26
	v_lshl_add_u64 v[192:193], v[192:193], 0, s[94:95]
	s_mov_b32 m0, s24
	s_nop 0
	global_load_lds_dwordx4 v[192:193], off
	v_lshl_add_u64 v[192:193], v[220:221], 0, s[94:95]
	s_add_i32 m0, s24, 0x2000
	s_add_i32 s24, s58, s26
	global_load_lds_dwordx4 v[192:193], off
	v_lshl_add_u64 v[192:193], v[224:225], 0, s[94:95]
	s_mov_b32 m0, s24
	s_nop 0
	global_load_lds_dwordx4 v[192:193], off
	v_lshl_add_u64 v[192:193], v[226:227], 0, s[94:95]
	s_add_i32 m0, s24, 0x2000
	s_nop 0
	global_load_lds_dwordx4 v[192:193], off
	s_waitcnt vmcnt(6)
	s_waitcnt lgkmcnt(0)
	v_mfma_f32_16x16x32_bf16 v[62:65], v[132:135], v[164:167], v[62:65]
	v_mfma_f32_16x16x32_bf16 v[62:65], v[136:139], v[168:171], v[62:65]
	s_barrier
	s_setprio 1
	v_mfma_f32_16x16x32_bf16 v[58:61], v[144:147], v[168:171], v[58:61]
	v_mfma_f32_16x16x32_bf16 v[58:61], v[140:143], v[164:167], v[58:61]
	v_mfma_f32_16x16x32_bf16 v[42:45], v[140:143], v[172:175], v[42:45]
	v_mfma_f32_16x16x32_bf16 v[42:45], v[144:147], v[176:179], v[42:45]
	v_mfma_f32_16x16x32_bf16 v[46:49], v[136:139], v[176:179], v[46:49]
	v_mfma_f32_16x16x32_bf16 v[46:49], v[132:135], v[172:175], v[46:49]
	v_mfma_f32_16x16x32_bf16 v[30:33], v[132:135], v[180:183], v[30:33]
	v_mfma_f32_16x16x32_bf16 v[30:33], v[136:139], v[184:187], v[30:33]
	v_mfma_f32_16x16x32_bf16 v[26:29], v[144:147], v[184:187], v[26:29]
	v_mfma_f32_16x16x32_bf16 v[26:29], v[140:143], v[180:183], v[26:29]
	v_mfma_f32_16x16x32_bf16 v[10:13], v[140:143], v[188:191], v[10:13]
	v_mfma_f32_16x16x32_bf16 v[10:13], v[144:147], v[216:219], v[10:13]
	v_mfma_f32_16x16x32_bf16 v[14:17], v[136:139], v[216:219], v[14:17]
	v_mfma_f32_16x16x32_bf16 v[14:17], v[132:135], v[188:191], v[14:17]
	v_mfma_f32_16x16x32_bf16 v[54:57], v[148:151], v[164:167], v[54:57]
	v_mfma_f32_16x16x32_bf16 v[54:57], v[152:155], v[168:171], v[54:57]
	v_mfma_f32_16x16x32_bf16 v[50:53], v[160:163], v[168:171], v[50:53]
	v_mfma_f32_16x16x32_bf16 v[50:53], v[156:159], v[164:167], v[50:53]
	v_mfma_f32_16x16x32_bf16 v[34:37], v[156:159], v[172:175], v[34:37]
	v_mfma_f32_16x16x32_bf16 v[34:37], v[160:163], v[176:179], v[34:37]
	v_mfma_f32_16x16x32_bf16 v[38:41], v[152:155], v[176:179], v[38:41]
	v_mfma_f32_16x16x32_bf16 v[38:41], v[148:151], v[172:175], v[38:41]
	v_mfma_f32_16x16x32_bf16 v[22:25], v[148:151], v[180:183], v[22:25]
	v_mfma_f32_16x16x32_bf16 v[22:25], v[152:155], v[184:187], v[22:25]
	v_mfma_f32_16x16x32_bf16 v[18:21], v[160:163], v[184:187], v[18:21]
	v_mfma_f32_16x16x32_bf16 v[18:21], v[156:159], v[180:183], v[18:21]
	v_mfma_f32_16x16x32_bf16 v[2:5], v[156:159], v[188:191], v[2:5]
	v_mfma_f32_16x16x32_bf16 v[2:5], v[160:163], v[216:219], v[2:5]
	v_mfma_f32_16x16x32_bf16 v[6:9], v[152:155], v[216:219], v[6:9]
	v_mfma_f32_16x16x32_bf16 v[6:9], v[148:151], v[188:191], v[6:9]
	s_setprio 0
	s_barrier
	s_and_b32 s24, s56, 6
	s_cmp_eq_u32 s24, 0
	s_cselect_b64 s[58:59], -1, 0
	s_cmp_ge_u32 s56, s53
	s_cselect_b64 s[24:25], -1, 0
	s_cmp_lt_u32 s56, s53
	s_cselect_b64 s[60:61], -1, 0
	s_and_b64 s[58:59], s[58:59], s[60:61]
	s_andn2_b64 vcc, exec, s[58:59]
	s_cbranch_vccnz .LBB0_768
	ds_read2_b32 v[132:133], v130 offset1:1
	s_waitcnt lgkmcnt(0)
	v_rcp_f32_e32 v131, v133
	s_nop 0
	v_mul_f32_e32 v132, v132, v131
	v_pk_mul_f32 v[128:129], v[128:129], v[132:133] op_sel_hi:[1,0]
	v_pk_mul_f32 v[126:127], v[126:127], v[132:133] op_sel_hi:[1,0]
	v_pk_mul_f32 v[124:125], v[124:125], v[132:133] op_sel_hi:[1,0]
	v_pk_mul_f32 v[122:123], v[122:123], v[132:133] op_sel_hi:[1,0]
	v_pk_mul_f32 v[120:121], v[120:121], v[132:133] op_sel_hi:[1,0]
	v_pk_mul_f32 v[118:119], v[118:119], v[132:133] op_sel_hi:[1,0]
	v_pk_mul_f32 v[116:117], v[116:117], v[132:133] op_sel_hi:[1,0]
	v_pk_mul_f32 v[114:115], v[114:115], v[132:133] op_sel_hi:[1,0]
	ds_read2_b32 v[132:133], v130 offset0:128 offset1:129
	s_waitcnt lgkmcnt(0)
	v_rcp_f32_e32 v131, v133
	s_nop 0
	v_mul_f32_e32 v132, v132, v131
	v_add_u32_e32 v131, 0x400, v130
	v_pk_mul_f32 v[112:113], v[112:113], v[132:133] op_sel_hi:[1,0]
	v_pk_mul_f32 v[110:111], v[110:111], v[132:133] op_sel_hi:[1,0]
	v_pk_mul_f32 v[108:109], v[108:109], v[132:133] op_sel_hi:[1,0]
	v_pk_mul_f32 v[106:107], v[106:107], v[132:133] op_sel_hi:[1,0]
	v_pk_mul_f32 v[104:105], v[104:105], v[132:133] op_sel_hi:[1,0]
	v_pk_mul_f32 v[102:103], v[102:103], v[132:133] op_sel_hi:[1,0]
	v_pk_mul_f32 v[100:101], v[100:101], v[132:133] op_sel_hi:[1,0]
	v_pk_mul_f32 v[98:99], v[98:99], v[132:133] op_sel_hi:[1,0]
	ds_read2_b32 v[132:133], v131 offset1:1
	s_waitcnt lgkmcnt(0)
	v_rcp_f32_e32 v131, v133
	s_nop 0
	v_mul_f32_e32 v132, v132, v131
	v_add_u32_e32 v131, 0x600, v130
	v_pk_mul_f32 v[96:97], v[96:97], v[132:133] op_sel_hi:[1,0]
	v_pk_mul_f32 v[94:95], v[94:95], v[132:133] op_sel_hi:[1,0]
	v_pk_mul_f32 v[92:93], v[92:93], v[132:133] op_sel_hi:[1,0]
	v_pk_mul_f32 v[90:91], v[90:91], v[132:133] op_sel_hi:[1,0]
	v_pk_mul_f32 v[88:89], v[88:89], v[132:133] op_sel_hi:[1,0]
	v_pk_mul_f32 v[86:87], v[86:87], v[132:133] op_sel_hi:[1,0]
	v_pk_mul_f32 v[84:85], v[84:85], v[132:133] op_sel_hi:[1,0]
	v_pk_mul_f32 v[82:83], v[82:83], v[132:133] op_sel_hi:[1,0]
	ds_read2_b32 v[132:133], v131 offset1:1
	s_waitcnt lgkmcnt(0)
	v_rcp_f32_e32 v131, v133
	s_nop 0
	v_mul_f32_e32 v132, v132, v131
	v_add_u32_e32 v131, 0x1000, v130
	v_pk_mul_f32 v[80:81], v[80:81], v[132:133] op_sel_hi:[1,0]
	v_pk_mul_f32 v[78:79], v[78:79], v[132:133] op_sel_hi:[1,0]
	v_pk_mul_f32 v[76:77], v[76:77], v[132:133] op_sel_hi:[1,0]
	v_pk_mul_f32 v[74:75], v[74:75], v[132:133] op_sel_hi:[1,0]
	v_pk_mul_f32 v[72:73], v[72:73], v[132:133] op_sel_hi:[1,0]
	v_pk_mul_f32 v[70:71], v[70:71], v[132:133] op_sel_hi:[1,0]
	v_pk_mul_f32 v[68:69], v[68:69], v[132:133] op_sel_hi:[1,0]
	v_pk_mul_f32 v[66:67], v[66:67], v[132:133] op_sel_hi:[1,0]
	ds_read2_b32 v[132:133], v131 offset1:1
	s_waitcnt lgkmcnt(0)
	v_rcp_f32_e32 v131, v133
	s_nop 0
	v_mul_f32_e32 v132, v132, v131
	v_add_u32_e32 v131, 0x1200, v130
	v_pk_mul_f32 v[64:65], v[64:65], v[132:133] op_sel_hi:[1,0]
	v_pk_mul_f32 v[62:63], v[62:63], v[132:133] op_sel_hi:[1,0]
	v_pk_mul_f32 v[60:61], v[60:61], v[132:133] op_sel_hi:[1,0]
	v_pk_mul_f32 v[58:59], v[58:59], v[132:133] op_sel_hi:[1,0]
	v_pk_mul_f32 v[56:57], v[56:57], v[132:133] op_sel_hi:[1,0]
	v_pk_mul_f32 v[54:55], v[54:55], v[132:133] op_sel_hi:[1,0]
	v_pk_mul_f32 v[52:53], v[52:53], v[132:133] op_sel_hi:[1,0]
	v_pk_mul_f32 v[50:51], v[50:51], v[132:133] op_sel_hi:[1,0]
	ds_read2_b32 v[132:133], v131 offset1:1
	s_waitcnt lgkmcnt(0)
	v_rcp_f32_e32 v131, v133
	s_nop 0
	v_mul_f32_e32 v132, v132, v131
	v_add_u32_e32 v131, 0x1400, v130
	v_pk_mul_f32 v[48:49], v[48:49], v[132:133] op_sel_hi:[1,0]
	v_pk_mul_f32 v[46:47], v[46:47], v[132:133] op_sel_hi:[1,0]
	v_pk_mul_f32 v[44:45], v[44:45], v[132:133] op_sel_hi:[1,0]
	v_pk_mul_f32 v[42:43], v[42:43], v[132:133] op_sel_hi:[1,0]
	v_pk_mul_f32 v[40:41], v[40:41], v[132:133] op_sel_hi:[1,0]
	v_pk_mul_f32 v[38:39], v[38:39], v[132:133] op_sel_hi:[1,0]
	v_pk_mul_f32 v[36:37], v[36:37], v[132:133] op_sel_hi:[1,0]
	v_pk_mul_f32 v[34:35], v[34:35], v[132:133] op_sel_hi:[1,0]
	ds_read2_b32 v[132:133], v131 offset1:1
	s_waitcnt lgkmcnt(0)
	v_rcp_f32_e32 v131, v133
	s_nop 0
	v_mul_f32_e32 v132, v132, v131
	v_add_u32_e32 v131, 0x1600, v130
	v_pk_mul_f32 v[32:33], v[32:33], v[132:133] op_sel_hi:[1,0]
	v_pk_mul_f32 v[30:31], v[30:31], v[132:133] op_sel_hi:[1,0]
	v_pk_mul_f32 v[28:29], v[28:29], v[132:133] op_sel_hi:[1,0]
	v_pk_mul_f32 v[26:27], v[26:27], v[132:133] op_sel_hi:[1,0]
	v_pk_mul_f32 v[24:25], v[24:25], v[132:133] op_sel_hi:[1,0]
	v_pk_mul_f32 v[22:23], v[22:23], v[132:133] op_sel_hi:[1,0]
	v_pk_mul_f32 v[20:21], v[20:21], v[132:133] op_sel_hi:[1,0]
	v_pk_mul_f32 v[18:19], v[18:19], v[132:133] op_sel_hi:[1,0]
	ds_read2_b32 v[132:133], v131 offset1:1
	s_waitcnt lgkmcnt(0)
	v_rcp_f32_e32 v131, v133
	s_nop 0
	v_mul_f32_e32 v132, v132, v131
	v_pk_mul_f32 v[16:17], v[16:17], v[132:133] op_sel_hi:[1,0]
	v_pk_mul_f32 v[14:15], v[14:15], v[132:133] op_sel_hi:[1,0]
	v_pk_mul_f32 v[12:13], v[12:13], v[132:133] op_sel_hi:[1,0]
	v_pk_mul_f32 v[10:11], v[10:11], v[132:133] op_sel_hi:[1,0]
	v_pk_mul_f32 v[8:9], v[8:9], v[132:133] op_sel_hi:[1,0]
	v_pk_mul_f32 v[6:7], v[6:7], v[132:133] op_sel_hi:[1,0]
	v_pk_mul_f32 v[4:5], v[4:5], v[132:133] op_sel_hi:[1,0]
	v_pk_mul_f32 v[2:3], v[2:3], v[132:133] op_sel_hi:[1,0]
	s_branch .LBB0_768

.LBB0_850:
	s_sub_u32 vcc_lo, s18, s12
	s_subb_u32 vcc_hi, s19, 0
	s_mov_b32 m0, s33
	s_nop 0
	global_load_lds_dwordx4 v210, vcc
	s_mov_b32 m0, s34
	s_nop 0
	global_load_lds_dwordx4 v212, vcc
	ds_read_b128 v[66:69], v198
	ds_read_b128 v[78:81], v198 offset:1024
	ds_read_b128 v[82:85], v198 offset:2048
	ds_read_b128 v[98:101], v198 offset:3072
	ds_read_b128 v[106:109], v198 offset:16384
	ds_read_b128 v[118:121], v198 offset:17408
	ds_read_b128 v[130:133], v198 offset:18432
	ds_read_b128 v[142:145], v198 offset:19456
	ds_read_b128 v[150:153], v234
	ds_read_b128 v[154:157], v234 offset:1024
	ds_read_b128 v[158:161], v234 offset:2048
	ds_read_b128 v[162:165], v234 offset:3072
	ds_read_b128 v[170:173], v234 offset:4096
	ds_read_b128 v[174:177], v234 offset:5120
	ds_read_b128 v[178:181], v234 offset:6144
	ds_read_b128 v[190:193], v234 offset:7168
	s_add_i32 s55, s20, 2
	s_add_u32 s56, s18, 0x80
	s_addc_u32 s21, s19, 0
	s_add_i32 s58, 0, 0x10000
	s_cmp_eq_u32 s35, s20
	s_cselect_b32 s21, s1, s21
	s_cselect_b32 s20, s0, s56
	s_cselect_b32 s57, s17, s54
	s_cselect_b32 s56, s16, s51
	s_add_i32 s59, 0, 0x14000
	s_add_i32 m0, s26, 0xc000
	s_nop 0
	global_load_lds_dwordx4 v210, s[18:19]
	s_add_i32 m0, s26, 0xe000
	s_nop 0
	global_load_lds_dwordx4 v212, s[18:19]
	s_waitcnt vmcnt(8)
	s_waitcnt lgkmcnt(0)
	v_mfma_f32_16x16x32_bf16 v[186:189], v[66:69], v[150:153], v[186:189]
	v_mfma_f32_16x16x32_bf16 v[186:189], v[78:81], v[154:157], v[186:189]
	s_barrier
	s_setprio 1
	v_mfma_f32_16x16x32_bf16 v[182:185], v[98:101], v[154:157], v[182:185]
	v_mfma_f32_16x16x32_bf16 v[182:185], v[82:85], v[150:153], v[182:185]
	v_mfma_f32_16x16x32_bf16 v[134:137], v[82:85], v[158:161], v[134:137]
	v_mfma_f32_16x16x32_bf16 v[134:137], v[98:101], v[162:165], v[134:137]
	v_mfma_f32_16x16x32_bf16 v[138:141], v[78:81], v[162:165], v[138:141]
	v_mfma_f32_16x16x32_bf16 v[138:141], v[66:69], v[158:161], v[138:141]
	v_mfma_f32_16x16x32_bf16 v[114:117], v[66:69], v[170:173], v[114:117]
	v_mfma_f32_16x16x32_bf16 v[114:117], v[78:81], v[174:177], v[114:117]
	v_mfma_f32_16x16x32_bf16 v[110:113], v[98:101], v[174:177], v[110:113]
	v_mfma_f32_16x16x32_bf16 v[110:113], v[82:85], v[170:173], v[110:113]
	v_mfma_f32_16x16x32_bf16 v[86:89], v[82:85], v[178:181], v[86:89]
	v_mfma_f32_16x16x32_bf16 v[86:89], v[98:101], v[190:193], v[86:89]
	v_mfma_f32_16x16x32_bf16 v[90:93], v[78:81], v[190:193], v[90:93]
	v_mfma_f32_16x16x32_bf16 v[90:93], v[66:69], v[178:181], v[90:93]
	v_mfma_f32_16x16x32_bf16 v[166:169], v[106:109], v[150:153], v[166:169]
	v_mfma_f32_16x16x32_bf16 v[166:169], v[118:121], v[154:157], v[166:169]
	v_mfma_f32_16x16x32_bf16 v[146:149], v[142:145], v[154:157], v[146:149]
	v_mfma_f32_16x16x32_bf16 v[146:149], v[130:133], v[150:153], v[146:149]
	v_mfma_f32_16x16x32_bf16 v[122:125], v[130:133], v[158:161], v[122:125]
	v_mfma_f32_16x16x32_bf16 v[122:125], v[142:145], v[162:165], v[122:125]
	v_mfma_f32_16x16x32_bf16 v[126:129], v[118:121], v[162:165], v[126:129]
	v_mfma_f32_16x16x32_bf16 v[126:129], v[106:109], v[158:161], v[126:129]
	v_mfma_f32_16x16x32_bf16 v[102:105], v[106:109], v[170:173], v[102:105]
	v_mfma_f32_16x16x32_bf16 v[102:105], v[118:121], v[174:177], v[102:105]
	v_mfma_f32_16x16x32_bf16 v[94:97], v[142:145], v[174:177], v[94:97]
	v_mfma_f32_16x16x32_bf16 v[94:97], v[130:133], v[170:173], v[94:97]
	v_mfma_f32_16x16x32_bf16 v[70:73], v[130:133], v[178:181], v[70:73]
	v_mfma_f32_16x16x32_bf16 v[70:73], v[142:145], v[190:193], v[70:73]
	v_mfma_f32_16x16x32_bf16 v[74:77], v[118:121], v[190:193], v[74:77]
	v_mfma_f32_16x16x32_bf16 v[74:77], v[106:109], v[178:181], v[74:77]
	s_setprio 0
	s_barrier
	ds_read_b128 v[150:153], v234 offset:16384
	ds_read_b128 v[154:157], v234 offset:17408
	ds_read_b128 v[158:161], v234 offset:18432
	ds_read_b128 v[162:165], v234 offset:19456
	ds_read_b128 v[170:173], v234 offset:20480
	ds_read_b128 v[174:177], v234 offset:21504
	ds_read_b128 v[178:181], v234 offset:22528
	ds_read_b128 v[190:193], v234 offset:23552
	s_add_i32 s58, s58, s24
	v_lshl_add_u64 v[214:215], s[56:57], 0, v[194:195]
	s_mov_b32 m0, s58
	s_nop 0
	global_load_lds_dwordx4 v194, s[56:57]
	s_add_i32 m0, s58, 0x2000
	v_lshl_add_u64 v[216:217], s[56:57], 0, v[204:205]
	s_add_u32 s56, s56, s12
	s_addc_u32 s57, s57, 0
	s_add_i32 s58, s59, s24
	global_load_lds_dwordx4 v[216:217], off
	v_lshl_add_u64 v[218:219], s[56:57], 0, v[194:195]
	s_mov_b32 m0, s58
	v_lshl_add_u64 v[220:221], s[56:57], 0, v[204:205]
	global_load_lds_dwordx4 v194, s[56:57]
	s_add_i32 m0, s58, 0x2000
	s_nop 0
	global_load_lds_dwordx4 v204, s[56:57]
	s_waitcnt vmcnt(6)
	s_waitcnt lgkmcnt(0)
	v_mfma_f32_16x16x32_bf16 v[62:65], v[66:69], v[150:153], v[62:65]
	v_mfma_f32_16x16x32_bf16 v[62:65], v[78:81], v[154:157], v[62:65]
	s_barrier
	s_setprio 1
	v_mfma_f32_16x16x32_bf16 v[58:61], v[98:101], v[154:157], v[58:61]
	v_mfma_f32_16x16x32_bf16 v[58:61], v[82:85], v[150:153], v[58:61]
	v_mfma_f32_16x16x32_bf16 v[42:45], v[82:85], v[158:161], v[42:45]
	v_mfma_f32_16x16x32_bf16 v[42:45], v[98:101], v[162:165], v[42:45]
	v_mfma_f32_16x16x32_bf16 v[46:49], v[78:81], v[162:165], v[46:49]
	v_mfma_f32_16x16x32_bf16 v[46:49], v[66:69], v[158:161], v[46:49]
	v_mfma_f32_16x16x32_bf16 v[30:33], v[66:69], v[170:173], v[30:33]
	v_mfma_f32_16x16x32_bf16 v[30:33], v[78:81], v[174:177], v[30:33]
	v_mfma_f32_16x16x32_bf16 v[26:29], v[98:101], v[174:177], v[26:29]
	v_mfma_f32_16x16x32_bf16 v[26:29], v[82:85], v[170:173], v[26:29]
	v_mfma_f32_16x16x32_bf16 v[10:13], v[82:85], v[178:181], v[10:13]
	v_mfma_f32_16x16x32_bf16 v[10:13], v[98:101], v[190:193], v[10:13]
	v_mfma_f32_16x16x32_bf16 v[14:17], v[78:81], v[190:193], v[14:17]
	v_mfma_f32_16x16x32_bf16 v[14:17], v[66:69], v[178:181], v[14:17]
	v_mfma_f32_16x16x32_bf16 v[54:57], v[106:109], v[150:153], v[54:57]
	v_mfma_f32_16x16x32_bf16 v[54:57], v[118:121], v[154:157], v[54:57]
	v_mfma_f32_16x16x32_bf16 v[50:53], v[142:145], v[154:157], v[50:53]
	v_mfma_f32_16x16x32_bf16 v[50:53], v[130:133], v[150:153], v[50:53]
	v_mfma_f32_16x16x32_bf16 v[34:37], v[130:133], v[158:161], v[34:37]
	v_mfma_f32_16x16x32_bf16 v[34:37], v[142:145], v[162:165], v[34:37]
	v_mfma_f32_16x16x32_bf16 v[38:41], v[118:121], v[162:165], v[38:41]
	v_mfma_f32_16x16x32_bf16 v[38:41], v[106:109], v[158:161], v[38:41]
	v_mfma_f32_16x16x32_bf16 v[22:25], v[106:109], v[170:173], v[22:25]
	v_mfma_f32_16x16x32_bf16 v[22:25], v[118:121], v[174:177], v[22:25]
	v_mfma_f32_16x16x32_bf16 v[18:21], v[142:145], v[174:177], v[18:21]
	v_mfma_f32_16x16x32_bf16 v[18:21], v[130:133], v[170:173], v[18:21]
	v_mfma_f32_16x16x32_bf16 v[2:5], v[130:133], v[178:181], v[2:5]
	v_mfma_f32_16x16x32_bf16 v[2:5], v[142:145], v[190:193], v[2:5]
	v_mfma_f32_16x16x32_bf16 v[6:9], v[118:121], v[190:193], v[6:9]
	v_mfma_f32_16x16x32_bf16 v[6:9], v[106:109], v[178:181], v[6:9]
	s_setprio 0
	s_barrier
	s_mov_b32 m0, s26
	s_nop 0
	global_load_lds_dwordx4 v208, s[20:21]
	s_mov_b32 m0, s27
	s_nop 0
	global_load_lds_dwordx4 v206, s[20:21]
	ds_read_b128 v[66:69], v198 offset:32768
	ds_read_b128 v[78:81], v198 offset:33792
	ds_read_b128 v[82:85], v198 offset:34816
	ds_read_b128 v[98:101], v198 offset:35840
	ds_read_b128 v[106:109], v198 offset:49152
	ds_read_b128 v[118:121], v198 offset:50176
	ds_read_b128 v[130:133], v198 offset:51200
	ds_read_b128 v[142:145], v198 offset:52224
	ds_read_b128 v[150:153], v234 offset:32768
	ds_read_b128 v[154:157], v234 offset:33792
	ds_read_b128 v[158:161], v234 offset:34816
	ds_read_b128 v[162:165], v234 offset:35840
	ds_read_b128 v[170:173], v234 offset:36864
	ds_read_b128 v[174:177], v234 offset:37888
	ds_read_b128 v[178:181], v234 offset:38912
	ds_read_b128 v[190:193], v234 offset:39936
	s_add_i32 s56, 0, 0x18000
	s_add_i32 s57, 0, 0x1c000
	s_add_u32 s20, s20, s12
	s_addc_u32 s21, s21, 0
	s_mov_b32 m0, s28
	s_nop 0
	global_load_lds_dwordx4 v208, s[20:21]
	s_mov_b32 m0, s29
	s_nop 0
	global_load_lds_dwordx4 v206, s[20:21]
	s_waitcnt vmcnt(8)
	s_waitcnt lgkmcnt(0)
	v_mfma_f32_16x16x32_bf16 v[186:189], v[66:69], v[150:153], v[186:189]
	v_mfma_f32_16x16x32_bf16 v[186:189], v[78:81], v[154:157], v[186:189]
	s_barrier
	s_setprio 1
	v_mfma_f32_16x16x32_bf16 v[182:185], v[98:101], v[154:157], v[182:185]
	v_mfma_f32_16x16x32_bf16 v[182:185], v[82:85], v[150:153], v[182:185]
	v_mfma_f32_16x16x32_bf16 v[134:137], v[82:85], v[158:161], v[134:137]
	v_mfma_f32_16x16x32_bf16 v[134:137], v[98:101], v[162:165], v[134:137]
	v_mfma_f32_16x16x32_bf16 v[138:141], v[78:81], v[162:165], v[138:141]
	v_mfma_f32_16x16x32_bf16 v[138:141], v[66:69], v[158:161], v[138:141]
	v_mfma_f32_16x16x32_bf16 v[114:117], v[66:69], v[170:173], v[114:117]
	v_mfma_f32_16x16x32_bf16 v[114:117], v[78:81], v[174:177], v[114:117]
	v_mfma_f32_16x16x32_bf16 v[110:113], v[98:101], v[174:177], v[110:113]
	v_mfma_f32_16x16x32_bf16 v[110:113], v[82:85], v[170:173], v[110:113]
	v_mfma_f32_16x16x32_bf16 v[86:89], v[82:85], v[178:181], v[86:89]
	v_mfma_f32_16x16x32_bf16 v[86:89], v[98:101], v[190:193], v[86:89]
	v_mfma_f32_16x16x32_bf16 v[90:93], v[78:81], v[190:193], v[90:93]
	v_mfma_f32_16x16x32_bf16 v[90:93], v[66:69], v[178:181], v[90:93]
	v_mfma_f32_16x16x32_bf16 v[166:169], v[106:109], v[150:153], v[166:169]
	v_mfma_f32_16x16x32_bf16 v[166:169], v[118:121], v[154:157], v[166:169]
	v_mfma_f32_16x16x32_bf16 v[146:149], v[142:145], v[154:157], v[146:149]
	v_mfma_f32_16x16x32_bf16 v[146:149], v[130:133], v[150:153], v[146:149]
	v_mfma_f32_16x16x32_bf16 v[122:125], v[130:133], v[158:161], v[122:125]
	v_mfma_f32_16x16x32_bf16 v[122:125], v[142:145], v[162:165], v[122:125]
	v_mfma_f32_16x16x32_bf16 v[126:129], v[118:121], v[162:165], v[126:129]
	v_mfma_f32_16x16x32_bf16 v[126:129], v[106:109], v[158:161], v[126:129]
	v_mfma_f32_16x16x32_bf16 v[102:105], v[106:109], v[170:173], v[102:105]
	v_mfma_f32_16x16x32_bf16 v[102:105], v[118:121], v[174:177], v[102:105]
	v_mfma_f32_16x16x32_bf16 v[94:97], v[142:145], v[174:177], v[94:97]
	v_mfma_f32_16x16x32_bf16 v[94:97], v[130:133], v[170:173], v[94:97]
	v_mfma_f32_16x16x32_bf16 v[70:73], v[130:133], v[178:181], v[70:73]
	v_mfma_f32_16x16x32_bf16 v[70:73], v[142:145], v[190:193], v[70:73]
	v_mfma_f32_16x16x32_bf16 v[74:77], v[118:121], v[190:193], v[74:77]
	v_mfma_f32_16x16x32_bf16 v[74:77], v[106:109], v[178:181], v[74:77]
	s_setprio 0
	s_barrier
	ds_read_b128 v[150:153], v234 offset:49152
	ds_read_b128 v[154:157], v234 offset:50176
	ds_read_b128 v[158:161], v234 offset:51200
	ds_read_b128 v[162:165], v234 offset:52224
	ds_read_b128 v[170:173], v234 offset:53248
	ds_read_b128 v[174:177], v234 offset:54272
	ds_read_b128 v[178:181], v234 offset:55296
	ds_read_b128 v[190:193], v234 offset:56320
	s_add_i32 s20, s56, s24
	v_lshl_add_u64 v[214:215], v[214:215], 0, s[94:95]
	s_mov_b32 m0, s20
	s_nop 0
	global_load_lds_dwordx4 v[214:215], off
	v_lshl_add_u64 v[214:215], v[216:217], 0, s[94:95]
	s_add_i32 m0, s20, 0x2000
	s_add_i32 s20, s57, s24
	global_load_lds_dwordx4 v[214:215], off
	v_lshl_add_u64 v[214:215], v[218:219], 0, s[94:95]
	s_mov_b32 m0, s20
	s_nop 0
	global_load_lds_dwordx4 v[214:215], off
	v_lshl_add_u64 v[214:215], v[220:221], 0, s[94:95]
	s_add_i32 m0, s20, 0x2000
	s_nop 0
	global_load_lds_dwordx4 v[214:215], off
	s_waitcnt vmcnt(6)
	s_waitcnt lgkmcnt(0)
	v_mfma_f32_16x16x32_bf16 v[62:65], v[66:69], v[150:153], v[62:65]
	v_mfma_f32_16x16x32_bf16 v[62:65], v[78:81], v[154:157], v[62:65]
	s_barrier
	s_setprio 1
	v_mfma_f32_16x16x32_bf16 v[58:61], v[98:101], v[154:157], v[58:61]
	v_mfma_f32_16x16x32_bf16 v[58:61], v[82:85], v[150:153], v[58:61]
	v_mfma_f32_16x16x32_bf16 v[42:45], v[82:85], v[158:161], v[42:45]
	v_mfma_f32_16x16x32_bf16 v[42:45], v[98:101], v[162:165], v[42:45]
	v_mfma_f32_16x16x32_bf16 v[46:49], v[78:81], v[162:165], v[46:49]
	v_mfma_f32_16x16x32_bf16 v[46:49], v[66:69], v[158:161], v[46:49]
	v_mfma_f32_16x16x32_bf16 v[30:33], v[66:69], v[170:173], v[30:33]
	v_mfma_f32_16x16x32_bf16 v[30:33], v[78:81], v[174:177], v[30:33]
	v_mfma_f32_16x16x32_bf16 v[26:29], v[98:101], v[174:177], v[26:29]
	v_mfma_f32_16x16x32_bf16 v[26:29], v[82:85], v[170:173], v[26:29]
	v_mfma_f32_16x16x32_bf16 v[10:13], v[82:85], v[178:181], v[10:13]
	v_mfma_f32_16x16x32_bf16 v[10:13], v[98:101], v[190:193], v[10:13]
	s_add_u32 s18, s18, 0x100
	v_mfma_f32_16x16x32_bf16 v[14:17], v[78:81], v[190:193], v[14:17]
	v_mfma_f32_16x16x32_bf16 v[14:17], v[66:69], v[178:181], v[14:17]
	s_addc_u32 s19, s19, 0
	v_mfma_f32_16x16x32_bf16 v[54:57], v[106:109], v[150:153], v[54:57]
	v_mfma_f32_16x16x32_bf16 v[54:57], v[118:121], v[154:157], v[54:57]
	s_add_u32 s51, s51, 0x100
	v_mfma_f32_16x16x32_bf16 v[50:53], v[142:145], v[154:157], v[50:53]
	v_mfma_f32_16x16x32_bf16 v[50:53], v[130:133], v[150:153], v[50:53]
	s_addc_u32 s54, s54, 0
	v_mfma_f32_16x16x32_bf16 v[34:37], v[130:133], v[158:161], v[34:37]
	v_mfma_f32_16x16x32_bf16 v[34:37], v[142:145], v[162:165], v[34:37]
	s_cmp_ge_u32 s55, s53
	v_mfma_f32_16x16x32_bf16 v[38:41], v[118:121], v[162:165], v[38:41]
	v_mfma_f32_16x16x32_bf16 v[38:41], v[106:109], v[158:161], v[38:41]
	s_mov_b32 s20, s55
	v_mfma_f32_16x16x32_bf16 v[22:25], v[106:109], v[170:173], v[22:25]
	v_mfma_f32_16x16x32_bf16 v[22:25], v[118:121], v[174:177], v[22:25]
	v_mfma_f32_16x16x32_bf16 v[18:21], v[142:145], v[174:177], v[18:21]
	v_mfma_f32_16x16x32_bf16 v[18:21], v[130:133], v[170:173], v[18:21]
	v_mfma_f32_16x16x32_bf16 v[2:5], v[130:133], v[178:181], v[2:5]
	v_mfma_f32_16x16x32_bf16 v[2:5], v[142:145], v[190:193], v[2:5]
	v_mfma_f32_16x16x32_bf16 v[6:9], v[118:121], v[190:193], v[6:9]
	v_mfma_f32_16x16x32_bf16 v[6:9], v[106:109], v[178:181], v[6:9]
	s_setprio 0
	s_barrier
	s_cbranch_scc0 .LBB0_850
	s_and_b64 vcc, exec, s[14:15]
	s_cbranch_vccz .LBB0_853
	s_barrier

.LBB0_875:
	s_sub_u32 vcc_lo, s20, s12
	s_subb_u32 vcc_hi, s21, 0
	s_mov_b32 m0, s51
	s_nop 0
	global_load_lds_dwordx4 v210, vcc
	s_mov_b32 m0, s53
	s_nop 0
	global_load_lds_dwordx4 v212, vcc
	ds_read_b128 v[130:133], v235
	ds_read_b128 v[134:137], v235 offset:1024
	ds_read_b128 v[138:141], v235 offset:2048
	ds_read_b128 v[142:145], v235 offset:3072
	ds_read_b128 v[146:149], v235 offset:16384
	ds_read_b128 v[150:153], v235 offset:17408
	ds_read_b128 v[154:157], v235 offset:18432
	ds_read_b128 v[158:161], v235 offset:19456
	ds_read_b128 v[162:165], v237
	ds_read_b128 v[166:169], v237 offset:1024
	ds_read_b128 v[170:173], v237 offset:2048
	ds_read_b128 v[174:177], v237 offset:3072
	ds_read_b128 v[178:181], v237 offset:4096
	ds_read_b128 v[182:185], v237 offset:5120
	ds_read_b128 v[186:189], v237 offset:6144
	ds_read_b128 v[190:193], v237 offset:7168
	s_add_i32 s29, s26, 2
	s_add_u32 s62, s20, 0x80
	s_addc_u32 s27, s21, 0
	s_add_i32 s64, 0, 0x10000
	s_cmp_eq_u32 s17, s26
	s_cselect_b32 s27, s7, s27
	s_cselect_b32 s26, s6, s62
	s_cselect_b32 s63, s19, s28
	s_cselect_b32 s62, s18, s23
	s_add_i32 s65, 0, 0x14000
	s_add_i32 m0, s37, 0xc000
	s_nop 0
	global_load_lds_dwordx4 v210, s[20:21]
	s_add_i32 m0, s37, 0xe000
	s_nop 0
	global_load_lds_dwordx4 v212, s[20:21]
	s_waitcnt vmcnt(8)
	s_waitcnt lgkmcnt(0)
	v_mfma_f32_16x16x32_bf16 v[126:129], v[130:133], v[162:165], v[126:129]
	v_mfma_f32_16x16x32_bf16 v[126:129], v[134:137], v[166:169], v[126:129]
	s_barrier
	s_setprio 1
	v_mfma_f32_16x16x32_bf16 v[122:125], v[142:145], v[166:169], v[122:125]
	v_mfma_f32_16x16x32_bf16 v[122:125], v[138:141], v[162:165], v[122:125]
	v_mfma_f32_16x16x32_bf16 v[106:109], v[138:141], v[170:173], v[106:109]
	v_mfma_f32_16x16x32_bf16 v[106:109], v[142:145], v[174:177], v[106:109]
	v_mfma_f32_16x16x32_bf16 v[110:113], v[134:137], v[174:177], v[110:113]
	v_mfma_f32_16x16x32_bf16 v[110:113], v[130:133], v[170:173], v[110:113]
	v_mfma_f32_16x16x32_bf16 v[94:97], v[130:133], v[178:181], v[94:97]
	v_mfma_f32_16x16x32_bf16 v[94:97], v[134:137], v[182:185], v[94:97]
	v_mfma_f32_16x16x32_bf16 v[90:93], v[142:145], v[182:185], v[90:93]
	v_mfma_f32_16x16x32_bf16 v[90:93], v[138:141], v[178:181], v[90:93]
	v_mfma_f32_16x16x32_bf16 v[74:77], v[138:141], v[186:189], v[74:77]
	v_mfma_f32_16x16x32_bf16 v[74:77], v[142:145], v[190:193], v[74:77]
	v_mfma_f32_16x16x32_bf16 v[78:81], v[134:137], v[190:193], v[78:81]
	v_mfma_f32_16x16x32_bf16 v[78:81], v[130:133], v[186:189], v[78:81]
	v_mfma_f32_16x16x32_bf16 v[118:121], v[146:149], v[162:165], v[118:121]
	v_mfma_f32_16x16x32_bf16 v[118:121], v[150:153], v[166:169], v[118:121]
	v_mfma_f32_16x16x32_bf16 v[114:117], v[158:161], v[166:169], v[114:117]
	v_mfma_f32_16x16x32_bf16 v[114:117], v[154:157], v[162:165], v[114:117]
	v_mfma_f32_16x16x32_bf16 v[98:101], v[154:157], v[170:173], v[98:101]
	v_mfma_f32_16x16x32_bf16 v[98:101], v[158:161], v[174:177], v[98:101]
	v_mfma_f32_16x16x32_bf16 v[102:105], v[150:153], v[174:177], v[102:105]
	v_mfma_f32_16x16x32_bf16 v[102:105], v[146:149], v[170:173], v[102:105]
	v_mfma_f32_16x16x32_bf16 v[86:89], v[146:149], v[178:181], v[86:89]
	v_mfma_f32_16x16x32_bf16 v[86:89], v[150:153], v[182:185], v[86:89]
	v_mfma_f32_16x16x32_bf16 v[82:85], v[158:161], v[182:185], v[82:85]
	v_mfma_f32_16x16x32_bf16 v[82:85], v[154:157], v[178:181], v[82:85]
	v_mfma_f32_16x16x32_bf16 v[66:69], v[154:157], v[186:189], v[66:69]
	v_mfma_f32_16x16x32_bf16 v[66:69], v[158:161], v[190:193], v[66:69]
	v_mfma_f32_16x16x32_bf16 v[70:73], v[150:153], v[190:193], v[70:73]
	v_mfma_f32_16x16x32_bf16 v[70:73], v[146:149], v[186:189], v[70:73]
	s_setprio 0
	s_barrier
	ds_read_b128 v[162:165], v237 offset:16384
	ds_read_b128 v[166:169], v237 offset:17408
	ds_read_b128 v[170:173], v237 offset:18432
	ds_read_b128 v[174:177], v237 offset:19456
	ds_read_b128 v[178:181], v237 offset:20480
	ds_read_b128 v[182:185], v237 offset:21504
	ds_read_b128 v[186:189], v237 offset:22528
	ds_read_b128 v[190:193], v237 offset:23552
	s_add_i32 s64, s64, s36
	v_lshl_add_u64 v[198:199], s[62:63], 0, v[194:195]
	s_mov_b32 m0, s64
	s_nop 0
	global_load_lds_dwordx4 v194, s[62:63]
	s_add_i32 m0, s64, 0x2000
	v_lshl_add_u64 v[214:215], s[62:63], 0, v[208:209]
	s_add_u32 s62, s62, s12
	s_addc_u32 s63, s63, 0
	s_add_i32 s64, s65, s36
	global_load_lds_dwordx4 v[214:215], off
	v_lshl_add_u64 v[216:217], s[62:63], 0, v[194:195]
	s_mov_b32 m0, s64
	v_lshl_add_u64 v[218:219], s[62:63], 0, v[208:209]
	global_load_lds_dwordx4 v194, s[62:63]
	s_add_i32 m0, s64, 0x2000
	s_nop 0
	global_load_lds_dwordx4 v208, s[62:63]
	s_waitcnt vmcnt(6)
	s_waitcnt lgkmcnt(0)
	v_mfma_f32_16x16x32_bf16 v[62:65], v[130:133], v[162:165], v[62:65]
	v_mfma_f32_16x16x32_bf16 v[62:65], v[134:137], v[166:169], v[62:65]
	s_barrier
	s_setprio 1
	v_mfma_f32_16x16x32_bf16 v[58:61], v[142:145], v[166:169], v[58:61]
	v_mfma_f32_16x16x32_bf16 v[58:61], v[138:141], v[162:165], v[58:61]
	v_mfma_f32_16x16x32_bf16 v[42:45], v[138:141], v[170:173], v[42:45]
	v_mfma_f32_16x16x32_bf16 v[42:45], v[142:145], v[174:177], v[42:45]
	v_mfma_f32_16x16x32_bf16 v[46:49], v[134:137], v[174:177], v[46:49]
	v_mfma_f32_16x16x32_bf16 v[46:49], v[130:133], v[170:173], v[46:49]
	v_mfma_f32_16x16x32_bf16 v[30:33], v[130:133], v[178:181], v[30:33]
	v_mfma_f32_16x16x32_bf16 v[30:33], v[134:137], v[182:185], v[30:33]
	v_mfma_f32_16x16x32_bf16 v[26:29], v[142:145], v[182:185], v[26:29]
	v_mfma_f32_16x16x32_bf16 v[26:29], v[138:141], v[178:181], v[26:29]
	v_mfma_f32_16x16x32_bf16 v[10:13], v[138:141], v[186:189], v[10:13]
	v_mfma_f32_16x16x32_bf16 v[10:13], v[142:145], v[190:193], v[10:13]
	v_mfma_f32_16x16x32_bf16 v[14:17], v[134:137], v[190:193], v[14:17]
	v_mfma_f32_16x16x32_bf16 v[14:17], v[130:133], v[186:189], v[14:17]
	v_mfma_f32_16x16x32_bf16 v[54:57], v[146:149], v[162:165], v[54:57]
	v_mfma_f32_16x16x32_bf16 v[54:57], v[150:153], v[166:169], v[54:57]
	v_mfma_f32_16x16x32_bf16 v[50:53], v[158:161], v[166:169], v[50:53]
	v_mfma_f32_16x16x32_bf16 v[50:53], v[154:157], v[162:165], v[50:53]
	v_mfma_f32_16x16x32_bf16 v[34:37], v[154:157], v[170:173], v[34:37]
	v_mfma_f32_16x16x32_bf16 v[34:37], v[158:161], v[174:177], v[34:37]
	v_mfma_f32_16x16x32_bf16 v[38:41], v[150:153], v[174:177], v[38:41]
	v_mfma_f32_16x16x32_bf16 v[38:41], v[146:149], v[170:173], v[38:41]
	v_mfma_f32_16x16x32_bf16 v[22:25], v[146:149], v[178:181], v[22:25]
	v_mfma_f32_16x16x32_bf16 v[22:25], v[150:153], v[182:185], v[22:25]
	v_mfma_f32_16x16x32_bf16 v[18:21], v[158:161], v[182:185], v[18:21]
	v_mfma_f32_16x16x32_bf16 v[18:21], v[154:157], v[178:181], v[18:21]
	v_mfma_f32_16x16x32_bf16 v[2:5], v[154:157], v[186:189], v[2:5]
	v_mfma_f32_16x16x32_bf16 v[2:5], v[158:161], v[190:193], v[2:5]
	v_mfma_f32_16x16x32_bf16 v[6:9], v[150:153], v[190:193], v[6:9]
	v_mfma_f32_16x16x32_bf16 v[6:9], v[146:149], v[186:189], v[6:9]
	s_setprio 0
	s_barrier
	s_mov_b32 m0, s37
	s_nop 0
	global_load_lds_dwordx4 v204, s[26:27]
	s_mov_b32 m0, s38
	s_nop 0
	global_load_lds_dwordx4 v206, s[26:27]
	ds_read_b128 v[130:133], v235 offset:32768
	ds_read_b128 v[134:137], v235 offset:33792
	ds_read_b128 v[138:141], v235 offset:34816
	ds_read_b128 v[142:145], v235 offset:35840
	ds_read_b128 v[146:149], v235 offset:49152
	ds_read_b128 v[150:153], v235 offset:50176
	ds_read_b128 v[154:157], v235 offset:51200
	ds_read_b128 v[158:161], v235 offset:52224
	ds_read_b128 v[162:165], v237 offset:32768
	ds_read_b128 v[166:169], v237 offset:33792
	ds_read_b128 v[170:173], v237 offset:34816
	ds_read_b128 v[174:177], v237 offset:35840
	ds_read_b128 v[178:181], v237 offset:36864
	ds_read_b128 v[182:185], v237 offset:37888
	ds_read_b128 v[186:189], v237 offset:38912
	ds_read_b128 v[190:193], v237 offset:39936
	s_add_i32 s62, 0, 0x18000
	s_add_i32 s63, 0, 0x1c000
	s_add_u32 s26, s26, s12
	s_addc_u32 s27, s27, 0
	s_mov_b32 m0, s39
	s_nop 0
	global_load_lds_dwordx4 v204, s[26:27]
	s_mov_b32 m0, s50
	s_nop 0
	global_load_lds_dwordx4 v206, s[26:27]
	s_waitcnt vmcnt(8)
	s_waitcnt lgkmcnt(0)
	v_mfma_f32_16x16x32_bf16 v[126:129], v[130:133], v[162:165], v[126:129]
	v_mfma_f32_16x16x32_bf16 v[126:129], v[134:137], v[166:169], v[126:129]
	s_barrier
	s_setprio 1
	v_mfma_f32_16x16x32_bf16 v[122:125], v[142:145], v[166:169], v[122:125]
	v_mfma_f32_16x16x32_bf16 v[122:125], v[138:141], v[162:165], v[122:125]
	v_mfma_f32_16x16x32_bf16 v[106:109], v[138:141], v[170:173], v[106:109]
	v_mfma_f32_16x16x32_bf16 v[106:109], v[142:145], v[174:177], v[106:109]
	v_mfma_f32_16x16x32_bf16 v[110:113], v[134:137], v[174:177], v[110:113]
	v_mfma_f32_16x16x32_bf16 v[110:113], v[130:133], v[170:173], v[110:113]
	v_mfma_f32_16x16x32_bf16 v[94:97], v[130:133], v[178:181], v[94:97]
	v_mfma_f32_16x16x32_bf16 v[94:97], v[134:137], v[182:185], v[94:97]
	v_mfma_f32_16x16x32_bf16 v[90:93], v[142:145], v[182:185], v[90:93]
	v_mfma_f32_16x16x32_bf16 v[90:93], v[138:141], v[178:181], v[90:93]
	v_mfma_f32_16x16x32_bf16 v[74:77], v[138:141], v[186:189], v[74:77]
	v_mfma_f32_16x16x32_bf16 v[74:77], v[142:145], v[190:193], v[74:77]
	v_mfma_f32_16x16x32_bf16 v[78:81], v[134:137], v[190:193], v[78:81]
	v_mfma_f32_16x16x32_bf16 v[78:81], v[130:133], v[186:189], v[78:81]
	v_mfma_f32_16x16x32_bf16 v[118:121], v[146:149], v[162:165], v[118:121]
	v_mfma_f32_16x16x32_bf16 v[118:121], v[150:153], v[166:169], v[118:121]
	v_mfma_f32_16x16x32_bf16 v[114:117], v[158:161], v[166:169], v[114:117]
	v_mfma_f32_16x16x32_bf16 v[114:117], v[154:157], v[162:165], v[114:117]
	v_mfma_f32_16x16x32_bf16 v[98:101], v[154:157], v[170:173], v[98:101]
	v_mfma_f32_16x16x32_bf16 v[98:101], v[158:161], v[174:177], v[98:101]
	v_mfma_f32_16x16x32_bf16 v[102:105], v[150:153], v[174:177], v[102:105]
	v_mfma_f32_16x16x32_bf16 v[102:105], v[146:149], v[170:173], v[102:105]
	v_mfma_f32_16x16x32_bf16 v[86:89], v[146:149], v[178:181], v[86:89]
	v_mfma_f32_16x16x32_bf16 v[86:89], v[150:153], v[182:185], v[86:89]
	v_mfma_f32_16x16x32_bf16 v[82:85], v[158:161], v[182:185], v[82:85]
	v_mfma_f32_16x16x32_bf16 v[82:85], v[154:157], v[178:181], v[82:85]
	v_mfma_f32_16x16x32_bf16 v[66:69], v[154:157], v[186:189], v[66:69]
	v_mfma_f32_16x16x32_bf16 v[66:69], v[158:161], v[190:193], v[66:69]
	v_mfma_f32_16x16x32_bf16 v[70:73], v[150:153], v[190:193], v[70:73]
	v_mfma_f32_16x16x32_bf16 v[70:73], v[146:149], v[186:189], v[70:73]
	s_setprio 0
	s_barrier
	ds_read_b128 v[162:165], v237 offset:49152
	ds_read_b128 v[166:169], v237 offset:50176
	ds_read_b128 v[170:173], v237 offset:51200
	ds_read_b128 v[174:177], v237 offset:52224
	ds_read_b128 v[178:181], v237 offset:53248
	ds_read_b128 v[182:185], v237 offset:54272
	ds_read_b128 v[186:189], v237 offset:55296
	ds_read_b128 v[190:193], v237 offset:56320
	s_add_i32 s26, s62, s36
	v_lshl_add_u64 v[198:199], v[198:199], 0, s[94:95]
	s_mov_b32 m0, s26
	s_nop 0
	global_load_lds_dwordx4 v[198:199], off
	v_lshl_add_u64 v[198:199], v[214:215], 0, s[94:95]
	s_add_i32 m0, s26, 0x2000
	s_add_i32 s26, s63, s36
	global_load_lds_dwordx4 v[198:199], off
	v_lshl_add_u64 v[198:199], v[216:217], 0, s[94:95]
	s_mov_b32 m0, s26
	s_nop 0
	global_load_lds_dwordx4 v[198:199], off
	v_lshl_add_u64 v[198:199], v[218:219], 0, s[94:95]
	s_add_i32 m0, s26, 0x2000
	s_nop 0
	global_load_lds_dwordx4 v[198:199], off
	s_waitcnt vmcnt(6)
	s_waitcnt lgkmcnt(0)
	v_mfma_f32_16x16x32_bf16 v[62:65], v[130:133], v[162:165], v[62:65]
	v_mfma_f32_16x16x32_bf16 v[62:65], v[134:137], v[166:169], v[62:65]
	s_barrier
	s_setprio 1
	v_mfma_f32_16x16x32_bf16 v[58:61], v[142:145], v[166:169], v[58:61]
	v_mfma_f32_16x16x32_bf16 v[58:61], v[138:141], v[162:165], v[58:61]
	v_mfma_f32_16x16x32_bf16 v[42:45], v[138:141], v[170:173], v[42:45]
	v_mfma_f32_16x16x32_bf16 v[42:45], v[142:145], v[174:177], v[42:45]
	v_mfma_f32_16x16x32_bf16 v[46:49], v[134:137], v[174:177], v[46:49]
	v_mfma_f32_16x16x32_bf16 v[46:49], v[130:133], v[170:173], v[46:49]
	v_mfma_f32_16x16x32_bf16 v[30:33], v[130:133], v[178:181], v[30:33]
	v_mfma_f32_16x16x32_bf16 v[30:33], v[134:137], v[182:185], v[30:33]
	v_mfma_f32_16x16x32_bf16 v[26:29], v[142:145], v[182:185], v[26:29]
	v_mfma_f32_16x16x32_bf16 v[26:29], v[138:141], v[178:181], v[26:29]
	v_mfma_f32_16x16x32_bf16 v[10:13], v[138:141], v[186:189], v[10:13]
	v_mfma_f32_16x16x32_bf16 v[10:13], v[142:145], v[190:193], v[10:13]
	s_add_u32 s20, s20, 0x100
	v_mfma_f32_16x16x32_bf16 v[14:17], v[134:137], v[190:193], v[14:17]
	v_mfma_f32_16x16x32_bf16 v[14:17], v[130:133], v[186:189], v[14:17]
	s_addc_u32 s21, s21, 0
	v_mfma_f32_16x16x32_bf16 v[54:57], v[146:149], v[162:165], v[54:57]
	v_mfma_f32_16x16x32_bf16 v[54:57], v[150:153], v[166:169], v[54:57]
	s_add_u32 s23, s23, 0x100
	v_mfma_f32_16x16x32_bf16 v[50:53], v[158:161], v[166:169], v[50:53]
	v_mfma_f32_16x16x32_bf16 v[50:53], v[154:157], v[162:165], v[50:53]
	s_addc_u32 s28, s28, 0
	v_mfma_f32_16x16x32_bf16 v[34:37], v[154:157], v[170:173], v[34:37]
	v_mfma_f32_16x16x32_bf16 v[34:37], v[158:161], v[174:177], v[34:37]
	s_cmp_ge_i32 s29, s25
	v_mfma_f32_16x16x32_bf16 v[38:41], v[150:153], v[174:177], v[38:41]
	v_mfma_f32_16x16x32_bf16 v[38:41], v[146:149], v[170:173], v[38:41]
	s_mov_b32 s26, s29
	v_mfma_f32_16x16x32_bf16 v[22:25], v[146:149], v[178:181], v[22:25]
	v_mfma_f32_16x16x32_bf16 v[22:25], v[150:153], v[182:185], v[22:25]
	v_mfma_f32_16x16x32_bf16 v[18:21], v[158:161], v[182:185], v[18:21]
	v_mfma_f32_16x16x32_bf16 v[18:21], v[154:157], v[178:181], v[18:21]
	v_mfma_f32_16x16x32_bf16 v[2:5], v[154:157], v[186:189], v[2:5]
	v_mfma_f32_16x16x32_bf16 v[2:5], v[158:161], v[190:193], v[2:5]
	v_mfma_f32_16x16x32_bf16 v[6:9], v[150:153], v[190:193], v[6:9]
	v_mfma_f32_16x16x32_bf16 v[6:9], v[146:149], v[186:189], v[6:9]
	s_setprio 0
	s_barrier
	s_cbranch_scc0 .LBB0_875
	v_readlane_b32 s64, v254, 51
	v_readlane_b32 s65, v254, 52
	s_branch .LBB0_878

.LBB0_973:
	s_add_u32 vcc_lo, s0, 0xffffc000
	s_addc_u32 vcc_hi, s1, -1
	s_mov_b32 m0, s59
	s_nop 0
	global_load_lds_dwordx4 v146, vcc
	s_mov_b32 m0, s60
	s_nop 0
	global_load_lds_dwordx4 v148, vcc
	ds_read_b128 v[130:133], v246
	ds_read_b128 v[134:137], v246 offset:1024
	ds_read_b128 v[150:153], v246 offset:2048
	ds_read_b128 v[154:157], v246 offset:3072
	ds_read_b128 v[158:161], v246 offset:16384
	ds_read_b128 v[162:165], v246 offset:17408
	ds_read_b128 v[166:169], v246 offset:18432
	ds_read_b128 v[170:173], v246 offset:19456
	ds_read_b128 v[174:177], v247
	ds_read_b128 v[178:181], v247 offset:1024
	ds_read_b128 v[182:185], v247 offset:2048
	ds_read_b128 v[186:189], v247 offset:3072
	ds_read_b128 v[190:193], v247 offset:4096
	ds_read_b128 v[204:207], v247 offset:5120
	ds_read_b128 v[208:211], v247 offset:6144
	ds_read_b128 v[212:215], v247 offset:7168
	s_add_u32 s4, s0, 0x100
	s_addc_u32 s5, s1, 0
	s_add_i32 s40, 0, 0x10000
	s_cmp_eq_u32 s39, 28
	s_cselect_b32 s11, s35, s5
	s_cselect_b32 s10, s34, s4
	s_cselect_b32 s7, s13, s38
	s_cselect_b32 s6, s29, s33
	s_add_i32 s41, 0, 0x14000
	s_add_i32 m0, s49, 0xc000
	s_nop 0
	global_load_lds_dwordx4 v146, s[0:1]
	s_add_i32 m0, s49, 0xe000
	s_nop 0
	global_load_lds_dwordx4 v148, s[0:1]
	s_waitcnt vmcnt(8)
	s_waitcnt lgkmcnt(0)
	v_mfma_f32_16x16x32_bf16 v[126:129], v[130:133], v[174:177], v[126:129]
	v_mfma_f32_16x16x32_bf16 v[126:129], v[134:137], v[178:181], v[126:129]
	s_barrier
	s_setprio 1
	v_mfma_f32_16x16x32_bf16 v[62:65], v[154:157], v[178:181], v[62:65]
	v_mfma_f32_16x16x32_bf16 v[62:65], v[150:153], v[174:177], v[62:65]
	v_mfma_f32_16x16x32_bf16 v[58:61], v[150:153], v[182:185], v[58:61]
	v_mfma_f32_16x16x32_bf16 v[58:61], v[154:157], v[186:189], v[58:61]
	v_mfma_f32_16x16x32_bf16 v[122:125], v[134:137], v[186:189], v[122:125]
	v_mfma_f32_16x16x32_bf16 v[122:125], v[130:133], v[182:185], v[122:125]
	v_mfma_f32_16x16x32_bf16 v[114:117], v[130:133], v[190:193], v[114:117]
	v_mfma_f32_16x16x32_bf16 v[114:117], v[134:137], v[204:207], v[114:117]
	v_mfma_f32_16x16x32_bf16 v[50:53], v[154:157], v[204:207], v[50:53]
	v_mfma_f32_16x16x32_bf16 v[50:53], v[150:153], v[190:193], v[50:53]
	v_mfma_f32_16x16x32_bf16 v[42:45], v[150:153], v[208:211], v[42:45]
	v_mfma_f32_16x16x32_bf16 v[42:45], v[154:157], v[212:215], v[42:45]
	v_mfma_f32_16x16x32_bf16 v[106:109], v[134:137], v[212:215], v[106:109]
	v_mfma_f32_16x16x32_bf16 v[106:109], v[130:133], v[208:211], v[106:109]
	v_mfma_f32_16x16x32_bf16 v[118:121], v[158:161], v[174:177], v[118:121]
	v_mfma_f32_16x16x32_bf16 v[118:121], v[162:165], v[178:181], v[118:121]
	v_mfma_f32_16x16x32_bf16 v[54:57], v[170:173], v[178:181], v[54:57]
	v_mfma_f32_16x16x32_bf16 v[54:57], v[166:169], v[174:177], v[54:57]
	v_mfma_f32_16x16x32_bf16 v[46:49], v[166:169], v[182:185], v[46:49]
	v_mfma_f32_16x16x32_bf16 v[46:49], v[170:173], v[186:189], v[46:49]
	v_mfma_f32_16x16x32_bf16 v[110:113], v[162:165], v[186:189], v[110:113]
	v_mfma_f32_16x16x32_bf16 v[110:113], v[158:161], v[182:185], v[110:113]
	v_mfma_f32_16x16x32_bf16 v[102:105], v[158:161], v[190:193], v[102:105]
	v_mfma_f32_16x16x32_bf16 v[102:105], v[162:165], v[204:207], v[102:105]
	v_mfma_f32_16x16x32_bf16 v[38:41], v[170:173], v[204:207], v[38:41]
	v_mfma_f32_16x16x32_bf16 v[38:41], v[166:169], v[190:193], v[38:41]
	v_mfma_f32_16x16x32_bf16 v[34:37], v[166:169], v[208:211], v[34:37]
	v_mfma_f32_16x16x32_bf16 v[34:37], v[170:173], v[212:215], v[34:37]
	v_mfma_f32_16x16x32_bf16 v[98:101], v[162:165], v[212:215], v[98:101]
	v_mfma_f32_16x16x32_bf16 v[98:101], v[158:161], v[208:211], v[98:101]
	s_setprio 0
	s_barrier
	ds_read_b128 v[174:177], v247 offset:16384
	ds_read_b128 v[178:181], v247 offset:17408
	ds_read_b128 v[182:185], v247 offset:18432
	ds_read_b128 v[186:189], v247 offset:19456
	ds_read_b128 v[190:193], v247 offset:20480
	ds_read_b128 v[204:207], v247 offset:21504
	ds_read_b128 v[208:211], v247 offset:22528
	ds_read_b128 v[212:215], v247 offset:23552
	s_add_i32 s0, s40, s48
	s_mov_b32 m0, s0
	s_nop 0
	global_load_lds_dwordx4 v140, s[6:7]
	s_add_i32 m0, s0, 0x2000
	s_add_u32 s0, s6, 0x80000
	s_addc_u32 s1, s7, 0
	s_add_i32 s40, s41, s48
	global_load_lds_dwordx4 v144, s[6:7]
	s_mov_b32 m0, s40
	s_nop 0
	global_load_lds_dwordx4 v140, s[0:1]
	s_add_i32 m0, s40, 0x2000
	s_nop 0
	global_load_lds_dwordx4 v144, s[0:1]
	s_waitcnt vmcnt(6)
	s_waitcnt lgkmcnt(0)
	v_mfma_f32_16x16x32_bf16 v[94:97], v[130:133], v[174:177], v[94:97]
	v_mfma_f32_16x16x32_bf16 v[94:97], v[134:137], v[178:181], v[94:97]
	s_barrier
	s_setprio 1
	v_mfma_f32_16x16x32_bf16 v[30:33], v[154:157], v[178:181], v[30:33]
	v_mfma_f32_16x16x32_bf16 v[30:33], v[150:153], v[174:177], v[30:33]
	v_mfma_f32_16x16x32_bf16 v[26:29], v[150:153], v[182:185], v[26:29]
	v_mfma_f32_16x16x32_bf16 v[26:29], v[154:157], v[186:189], v[26:29]
	v_mfma_f32_16x16x32_bf16 v[90:93], v[134:137], v[186:189], v[90:93]
	v_mfma_f32_16x16x32_bf16 v[90:93], v[130:133], v[182:185], v[90:93]
	v_mfma_f32_16x16x32_bf16 v[82:85], v[130:133], v[190:193], v[82:85]
	v_mfma_f32_16x16x32_bf16 v[82:85], v[134:137], v[204:207], v[82:85]
	v_mfma_f32_16x16x32_bf16 v[18:21], v[154:157], v[204:207], v[18:21]
	v_mfma_f32_16x16x32_bf16 v[18:21], v[150:153], v[190:193], v[18:21]
	v_mfma_f32_16x16x32_bf16 v[10:13], v[150:153], v[208:211], v[10:13]
	v_mfma_f32_16x16x32_bf16 v[10:13], v[154:157], v[212:215], v[10:13]
	v_mfma_f32_16x16x32_bf16 v[74:77], v[134:137], v[212:215], v[74:77]
	v_mfma_f32_16x16x32_bf16 v[74:77], v[130:133], v[208:211], v[74:77]
	v_mfma_f32_16x16x32_bf16 v[86:89], v[158:161], v[174:177], v[86:89]
	v_mfma_f32_16x16x32_bf16 v[86:89], v[162:165], v[178:181], v[86:89]
	v_mfma_f32_16x16x32_bf16 v[22:25], v[170:173], v[178:181], v[22:25]
	v_mfma_f32_16x16x32_bf16 v[22:25], v[166:169], v[174:177], v[22:25]
	v_mfma_f32_16x16x32_bf16 v[14:17], v[166:169], v[182:185], v[14:17]
	v_mfma_f32_16x16x32_bf16 v[14:17], v[170:173], v[186:189], v[14:17]
	v_mfma_f32_16x16x32_bf16 v[78:81], v[162:165], v[186:189], v[78:81]
	v_mfma_f32_16x16x32_bf16 v[78:81], v[158:161], v[182:185], v[78:81]
	v_mfma_f32_16x16x32_bf16 v[70:73], v[158:161], v[190:193], v[70:73]
	v_mfma_f32_16x16x32_bf16 v[70:73], v[162:165], v[204:207], v[70:73]
	v_mfma_f32_16x16x32_bf16 v[6:9], v[170:173], v[204:207], v[6:9]
	v_mfma_f32_16x16x32_bf16 v[6:9], v[166:169], v[190:193], v[6:9]
	v_mfma_f32_16x16x32_bf16 v[2:5], v[166:169], v[208:211], v[2:5]
	v_mfma_f32_16x16x32_bf16 v[2:5], v[170:173], v[212:215], v[2:5]
	v_mfma_f32_16x16x32_bf16 v[66:69], v[162:165], v[212:215], v[66:69]
	v_mfma_f32_16x16x32_bf16 v[66:69], v[158:161], v[208:211], v[66:69]
	s_setprio 0
	s_barrier
	s_mov_b32 m0, s49
	s_nop 0
	global_load_lds_dwordx4 v138, s[10:11]
	s_mov_b32 m0, s70
	s_nop 0
	global_load_lds_dwordx4 v142, s[10:11]
	ds_read_b128 v[130:133], v246 offset:32768
	ds_read_b128 v[134:137], v246 offset:33792
	ds_read_b128 v[150:153], v246 offset:34816
	ds_read_b128 v[154:157], v246 offset:35840
	ds_read_b128 v[158:161], v246 offset:49152
	ds_read_b128 v[162:165], v246 offset:50176
	ds_read_b128 v[166:169], v246 offset:51200
	ds_read_b128 v[170:173], v246 offset:52224
	ds_read_b128 v[174:177], v247 offset:32768
	ds_read_b128 v[178:181], v247 offset:33792
	ds_read_b128 v[182:185], v247 offset:34816
	ds_read_b128 v[186:189], v247 offset:35840
	ds_read_b128 v[190:193], v247 offset:36864
	ds_read_b128 v[204:207], v247 offset:37888
	ds_read_b128 v[208:211], v247 offset:38912
	ds_read_b128 v[212:215], v247 offset:39936
	s_add_i32 s40, 0, 0x18000
	s_add_i32 s41, 0, 0x1c000
	s_add_u32 s0, s10, 0x4000
	s_addc_u32 s1, s11, 0
	s_mov_b32 m0, s71
	s_nop 0
	global_load_lds_dwordx4 v138, s[0:1]
	s_mov_b32 m0, s73
	s_nop 0
	global_load_lds_dwordx4 v142, s[0:1]
	s_waitcnt vmcnt(8)
	s_waitcnt lgkmcnt(0)
	v_mfma_f32_16x16x32_bf16 v[126:129], v[130:133], v[174:177], v[126:129]
	v_mfma_f32_16x16x32_bf16 v[126:129], v[134:137], v[178:181], v[126:129]
	s_barrier
	s_setprio 1
	v_mfma_f32_16x16x32_bf16 v[62:65], v[154:157], v[178:181], v[62:65]
	v_mfma_f32_16x16x32_bf16 v[62:65], v[150:153], v[174:177], v[62:65]
	v_mfma_f32_16x16x32_bf16 v[58:61], v[150:153], v[182:185], v[58:61]
	v_mfma_f32_16x16x32_bf16 v[58:61], v[154:157], v[186:189], v[58:61]
	v_mfma_f32_16x16x32_bf16 v[122:125], v[134:137], v[186:189], v[122:125]
	v_mfma_f32_16x16x32_bf16 v[122:125], v[130:133], v[182:185], v[122:125]
	v_mfma_f32_16x16x32_bf16 v[114:117], v[130:133], v[190:193], v[114:117]
	v_mfma_f32_16x16x32_bf16 v[114:117], v[134:137], v[204:207], v[114:117]
	v_mfma_f32_16x16x32_bf16 v[50:53], v[154:157], v[204:207], v[50:53]
	v_mfma_f32_16x16x32_bf16 v[50:53], v[150:153], v[190:193], v[50:53]
	v_mfma_f32_16x16x32_bf16 v[42:45], v[150:153], v[208:211], v[42:45]
	v_mfma_f32_16x16x32_bf16 v[42:45], v[154:157], v[212:215], v[42:45]
	v_mfma_f32_16x16x32_bf16 v[106:109], v[134:137], v[212:215], v[106:109]
	v_mfma_f32_16x16x32_bf16 v[106:109], v[130:133], v[208:211], v[106:109]
	v_mfma_f32_16x16x32_bf16 v[118:121], v[158:161], v[174:177], v[118:121]
	v_mfma_f32_16x16x32_bf16 v[118:121], v[162:165], v[178:181], v[118:121]
	v_mfma_f32_16x16x32_bf16 v[54:57], v[170:173], v[178:181], v[54:57]
	v_mfma_f32_16x16x32_bf16 v[54:57], v[166:169], v[174:177], v[54:57]
	v_mfma_f32_16x16x32_bf16 v[46:49], v[166:169], v[182:185], v[46:49]
	v_mfma_f32_16x16x32_bf16 v[46:49], v[170:173], v[186:189], v[46:49]
	v_mfma_f32_16x16x32_bf16 v[110:113], v[162:165], v[186:189], v[110:113]
	v_mfma_f32_16x16x32_bf16 v[110:113], v[158:161], v[182:185], v[110:113]
	v_mfma_f32_16x16x32_bf16 v[102:105], v[158:161], v[190:193], v[102:105]
	v_mfma_f32_16x16x32_bf16 v[102:105], v[162:165], v[204:207], v[102:105]
	v_mfma_f32_16x16x32_bf16 v[38:41], v[170:173], v[204:207], v[38:41]
	v_mfma_f32_16x16x32_bf16 v[38:41], v[166:169], v[190:193], v[38:41]
	v_mfma_f32_16x16x32_bf16 v[34:37], v[166:169], v[208:211], v[34:37]
	v_mfma_f32_16x16x32_bf16 v[34:37], v[170:173], v[212:215], v[34:37]
	v_mfma_f32_16x16x32_bf16 v[98:101], v[162:165], v[212:215], v[98:101]
	v_mfma_f32_16x16x32_bf16 v[98:101], v[158:161], v[208:211], v[98:101]
	s_setprio 0
	s_barrier
	ds_read_b128 v[174:177], v247 offset:49152
	ds_read_b128 v[178:181], v247 offset:50176
	ds_read_b128 v[182:185], v247 offset:51200
	ds_read_b128 v[186:189], v247 offset:52224
	ds_read_b128 v[190:193], v247 offset:53248
	ds_read_b128 v[204:207], v247 offset:54272
	ds_read_b128 v[208:211], v247 offset:55296
	ds_read_b128 v[212:215], v247 offset:56320
	s_add_i32 s0, s40, s48
	s_add_u32 vcc_lo, s6, s94
	s_addc_u32 vcc_hi, s7, s95
	s_mov_b32 m0, s0
	s_nop 0
	global_load_lds_dwordx4 v140, vcc
	s_add_i32 m0, s0, 0x2000
	s_add_u32 s0, s6, 0x80080
	s_addc_u32 s1, s7, 0
	s_add_i32 s6, s41, s48
	global_load_lds_dwordx4 v144, vcc
	s_mov_b32 m0, s6
	s_nop 0
	global_load_lds_dwordx4 v140, s[0:1]
	s_add_i32 m0, s6, 0x2000
	s_nop 0
	global_load_lds_dwordx4 v144, s[0:1]
	s_waitcnt vmcnt(6)
	s_waitcnt lgkmcnt(0)
	v_mfma_f32_16x16x32_bf16 v[94:97], v[130:133], v[174:177], v[94:97]
	v_mfma_f32_16x16x32_bf16 v[94:97], v[134:137], v[178:181], v[94:97]
	s_barrier
	s_setprio 1
	v_mfma_f32_16x16x32_bf16 v[30:33], v[154:157], v[178:181], v[30:33]
	v_mfma_f32_16x16x32_bf16 v[30:33], v[150:153], v[174:177], v[30:33]
	v_mfma_f32_16x16x32_bf16 v[26:29], v[150:153], v[182:185], v[26:29]
	v_mfma_f32_16x16x32_bf16 v[26:29], v[154:157], v[186:189], v[26:29]
	v_mfma_f32_16x16x32_bf16 v[90:93], v[134:137], v[186:189], v[90:93]
	v_mfma_f32_16x16x32_bf16 v[90:93], v[130:133], v[182:185], v[90:93]
	v_mfma_f32_16x16x32_bf16 v[82:85], v[130:133], v[190:193], v[82:85]
	v_mfma_f32_16x16x32_bf16 v[82:85], v[134:137], v[204:207], v[82:85]
	v_mfma_f32_16x16x32_bf16 v[18:21], v[154:157], v[204:207], v[18:21]
	v_mfma_f32_16x16x32_bf16 v[18:21], v[150:153], v[190:193], v[18:21]
	v_mfma_f32_16x16x32_bf16 v[10:13], v[150:153], v[208:211], v[10:13]
	v_mfma_f32_16x16x32_bf16 v[10:13], v[154:157], v[212:215], v[10:13]
	s_add_i32 s39, s39, 2
	v_mfma_f32_16x16x32_bf16 v[74:77], v[134:137], v[212:215], v[74:77]
	v_mfma_f32_16x16x32_bf16 v[74:77], v[130:133], v[208:211], v[74:77]
	s_add_u32 s33, s33, 0x100
	v_mfma_f32_16x16x32_bf16 v[86:89], v[158:161], v[174:177], v[86:89]
	v_mfma_f32_16x16x32_bf16 v[86:89], v[162:165], v[178:181], v[86:89]
	s_addc_u32 s38, s38, 0
	v_mfma_f32_16x16x32_bf16 v[22:25], v[170:173], v[178:181], v[22:25]
	v_mfma_f32_16x16x32_bf16 v[22:25], v[166:169], v[174:177], v[22:25]
	s_cmp_gt_u32 s39, 29
	v_mfma_f32_16x16x32_bf16 v[14:17], v[166:169], v[182:185], v[14:17]
	v_mfma_f32_16x16x32_bf16 v[14:17], v[170:173], v[186:189], v[14:17]
	s_mov_b64 s[0:1], s[4:5]
	v_mfma_f32_16x16x32_bf16 v[78:81], v[162:165], v[186:189], v[78:81]
	v_mfma_f32_16x16x32_bf16 v[78:81], v[158:161], v[182:185], v[78:81]
	v_mfma_f32_16x16x32_bf16 v[70:73], v[158:161], v[190:193], v[70:73]
	v_mfma_f32_16x16x32_bf16 v[70:73], v[162:165], v[204:207], v[70:73]
	v_mfma_f32_16x16x32_bf16 v[6:9], v[170:173], v[204:207], v[6:9]
	v_mfma_f32_16x16x32_bf16 v[6:9], v[166:169], v[190:193], v[6:9]
	v_mfma_f32_16x16x32_bf16 v[2:5], v[166:169], v[208:211], v[2:5]
	v_mfma_f32_16x16x32_bf16 v[2:5], v[170:173], v[212:215], v[2:5]
	v_mfma_f32_16x16x32_bf16 v[66:69], v[162:165], v[212:215], v[66:69]
	v_mfma_f32_16x16x32_bf16 v[66:69], v[158:161], v[208:211], v[66:69]
	s_setprio 0
	s_barrier
	s_cbranch_scc0 .LBB0_973
	s_and_b64 vcc, exec, s[26:27]
	s_cbranch_vccz .LBB0_976
	s_barrier

.LBB0_1441:
	s_add_u32 vcc_lo, s18, 0xffea0000
	s_addc_u32 vcc_hi, s19, -1
	s_mov_b32 m0, s38
	s_nop 0
	global_load_lds_dwordx4 v210, vcc
	s_mov_b32 m0, s40
	s_nop 0
	global_load_lds_dwordx4 v212, vcc
	ds_read_b128 v[66:69], v198
	ds_read_b128 v[78:81], v198 offset:1024
	ds_read_b128 v[86:89], v198 offset:2048
	ds_read_b128 v[98:101], v198 offset:3072
	ds_read_b128 v[106:109], v198 offset:16384
	ds_read_b128 v[118:121], v198 offset:17408
	ds_read_b128 v[130:133], v198 offset:18432
	ds_read_b128 v[142:145], v198 offset:19456
	ds_read_b128 v[150:153], v234
	ds_read_b128 v[154:157], v234 offset:1024
	ds_read_b128 v[158:161], v234 offset:2048
	ds_read_b128 v[162:165], v234 offset:3072
	ds_read_b128 v[170:173], v234 offset:4096
	ds_read_b128 v[174:177], v234 offset:5120
	ds_read_b128 v[178:181], v234 offset:6144
	ds_read_b128 v[190:193], v234 offset:7168
	s_add_u32 s20, s18, 0x100
	s_addc_u32 s21, s19, 0
	s_add_i32 s49, 0, 0x10000
	s_cmpk_eq_i32 s48, 0x54
	s_cselect_b32 s25, s1, s21
	s_cselect_b32 s24, s0, s20
	s_cselect_b32 s23, s17, s47
	s_cselect_b32 s22, s16, s46
	s_add_i32 s50, 0, 0x14000
	s_add_i32 m0, s28, 0xc000
	s_nop 0
	global_load_lds_dwordx4 v210, s[18:19]
	s_add_i32 m0, s28, 0xe000
	s_nop 0
	global_load_lds_dwordx4 v212, s[18:19]
	s_waitcnt vmcnt(8)
	s_waitcnt lgkmcnt(0)
	v_mfma_f32_16x16x32_bf16 v[186:189], v[66:69], v[150:153], v[186:189]
	v_mfma_f32_16x16x32_bf16 v[186:189], v[78:81], v[154:157], v[186:189]
	s_barrier
	s_setprio 1
	v_mfma_f32_16x16x32_bf16 v[182:185], v[98:101], v[154:157], v[182:185]
	v_mfma_f32_16x16x32_bf16 v[182:185], v[86:89], v[150:153], v[182:185]
	v_mfma_f32_16x16x32_bf16 v[134:137], v[86:89], v[158:161], v[134:137]
	v_mfma_f32_16x16x32_bf16 v[134:137], v[98:101], v[162:165], v[134:137]
	v_mfma_f32_16x16x32_bf16 v[138:141], v[78:81], v[162:165], v[138:141]
	v_mfma_f32_16x16x32_bf16 v[138:141], v[66:69], v[158:161], v[138:141]
	v_mfma_f32_16x16x32_bf16 v[114:117], v[66:69], v[170:173], v[114:117]
	v_mfma_f32_16x16x32_bf16 v[114:117], v[78:81], v[174:177], v[114:117]
	v_mfma_f32_16x16x32_bf16 v[110:113], v[98:101], v[174:177], v[110:113]
	v_mfma_f32_16x16x32_bf16 v[110:113], v[86:89], v[170:173], v[110:113]
	v_mfma_f32_16x16x32_bf16 v[82:85], v[86:89], v[178:181], v[82:85]
	v_mfma_f32_16x16x32_bf16 v[82:85], v[98:101], v[190:193], v[82:85]
	v_mfma_f32_16x16x32_bf16 v[90:93], v[78:81], v[190:193], v[90:93]
	v_mfma_f32_16x16x32_bf16 v[90:93], v[66:69], v[178:181], v[90:93]
	v_mfma_f32_16x16x32_bf16 v[166:169], v[106:109], v[150:153], v[166:169]
	v_mfma_f32_16x16x32_bf16 v[166:169], v[118:121], v[154:157], v[166:169]
	v_mfma_f32_16x16x32_bf16 v[146:149], v[142:145], v[154:157], v[146:149]
	v_mfma_f32_16x16x32_bf16 v[146:149], v[130:133], v[150:153], v[146:149]
	v_mfma_f32_16x16x32_bf16 v[122:125], v[130:133], v[158:161], v[122:125]
	v_mfma_f32_16x16x32_bf16 v[122:125], v[142:145], v[162:165], v[122:125]
	v_mfma_f32_16x16x32_bf16 v[126:129], v[118:121], v[162:165], v[126:129]
	v_mfma_f32_16x16x32_bf16 v[126:129], v[106:109], v[158:161], v[126:129]
	v_mfma_f32_16x16x32_bf16 v[102:105], v[106:109], v[170:173], v[102:105]
	v_mfma_f32_16x16x32_bf16 v[102:105], v[118:121], v[174:177], v[102:105]
	v_mfma_f32_16x16x32_bf16 v[94:97], v[142:145], v[174:177], v[94:97]
	v_mfma_f32_16x16x32_bf16 v[94:97], v[130:133], v[170:173], v[94:97]
	v_mfma_f32_16x16x32_bf16 v[70:73], v[130:133], v[178:181], v[70:73]
	v_mfma_f32_16x16x32_bf16 v[70:73], v[142:145], v[190:193], v[70:73]
	v_mfma_f32_16x16x32_bf16 v[74:77], v[118:121], v[190:193], v[74:77]
	v_mfma_f32_16x16x32_bf16 v[74:77], v[106:109], v[178:181], v[74:77]
	s_setprio 0
	s_barrier
	ds_read_b128 v[150:153], v234 offset:16384
	ds_read_b128 v[154:157], v234 offset:17408
	ds_read_b128 v[158:161], v234 offset:18432
	ds_read_b128 v[162:165], v234 offset:19456
	ds_read_b128 v[170:173], v234 offset:20480
	ds_read_b128 v[174:177], v234 offset:21504
	ds_read_b128 v[178:181], v234 offset:22528
	ds_read_b128 v[190:193], v234 offset:23552
	s_add_i32 s18, s49, s26
	s_mov_b32 m0, s18
	s_nop 0
	global_load_lds_dwordx4 v194, s[22:23]
	s_add_i32 m0, s18, 0x2000
	s_add_u32 s18, s22, 0x160000
	s_addc_u32 s19, s23, 0
	s_add_i32 s49, s50, s26
	global_load_lds_dwordx4 v204, s[22:23]
	s_mov_b32 m0, s49
	s_nop 0
	global_load_lds_dwordx4 v194, s[18:19]
	s_add_i32 m0, s49, 0x2000
	s_nop 0
	global_load_lds_dwordx4 v204, s[18:19]
	s_waitcnt vmcnt(6)
	s_waitcnt lgkmcnt(0)
	v_mfma_f32_16x16x32_bf16 v[62:65], v[66:69], v[150:153], v[62:65]
	v_mfma_f32_16x16x32_bf16 v[62:65], v[78:81], v[154:157], v[62:65]
	s_barrier
	s_setprio 1
	v_mfma_f32_16x16x32_bf16 v[58:61], v[98:101], v[154:157], v[58:61]
	v_mfma_f32_16x16x32_bf16 v[58:61], v[86:89], v[150:153], v[58:61]
	v_mfma_f32_16x16x32_bf16 v[42:45], v[86:89], v[158:161], v[42:45]
	v_mfma_f32_16x16x32_bf16 v[42:45], v[98:101], v[162:165], v[42:45]
	v_mfma_f32_16x16x32_bf16 v[46:49], v[78:81], v[162:165], v[46:49]
	v_mfma_f32_16x16x32_bf16 v[46:49], v[66:69], v[158:161], v[46:49]
	v_mfma_f32_16x16x32_bf16 v[30:33], v[66:69], v[170:173], v[30:33]
	v_mfma_f32_16x16x32_bf16 v[30:33], v[78:81], v[174:177], v[30:33]
	v_mfma_f32_16x16x32_bf16 v[26:29], v[98:101], v[174:177], v[26:29]
	v_mfma_f32_16x16x32_bf16 v[26:29], v[86:89], v[170:173], v[26:29]
	v_mfma_f32_16x16x32_bf16 v[10:13], v[86:89], v[178:181], v[10:13]
	v_mfma_f32_16x16x32_bf16 v[10:13], v[98:101], v[190:193], v[10:13]
	v_mfma_f32_16x16x32_bf16 v[14:17], v[78:81], v[190:193], v[14:17]
	v_mfma_f32_16x16x32_bf16 v[14:17], v[66:69], v[178:181], v[14:17]
	v_mfma_f32_16x16x32_bf16 v[54:57], v[106:109], v[150:153], v[54:57]
	v_mfma_f32_16x16x32_bf16 v[54:57], v[118:121], v[154:157], v[54:57]
	v_mfma_f32_16x16x32_bf16 v[50:53], v[142:145], v[154:157], v[50:53]
	v_mfma_f32_16x16x32_bf16 v[50:53], v[130:133], v[150:153], v[50:53]
	v_mfma_f32_16x16x32_bf16 v[34:37], v[130:133], v[158:161], v[34:37]
	v_mfma_f32_16x16x32_bf16 v[34:37], v[142:145], v[162:165], v[34:37]
	v_mfma_f32_16x16x32_bf16 v[38:41], v[118:121], v[162:165], v[38:41]
	v_mfma_f32_16x16x32_bf16 v[38:41], v[106:109], v[158:161], v[38:41]
	v_mfma_f32_16x16x32_bf16 v[22:25], v[106:109], v[170:173], v[22:25]
	v_mfma_f32_16x16x32_bf16 v[22:25], v[118:121], v[174:177], v[22:25]
	v_mfma_f32_16x16x32_bf16 v[18:21], v[142:145], v[174:177], v[18:21]
	v_mfma_f32_16x16x32_bf16 v[18:21], v[130:133], v[170:173], v[18:21]
	v_mfma_f32_16x16x32_bf16 v[2:5], v[130:133], v[178:181], v[2:5]
	v_mfma_f32_16x16x32_bf16 v[2:5], v[142:145], v[190:193], v[2:5]
	v_mfma_f32_16x16x32_bf16 v[6:9], v[118:121], v[190:193], v[6:9]
	v_mfma_f32_16x16x32_bf16 v[6:9], v[106:109], v[178:181], v[6:9]
	s_setprio 0
	s_barrier
	s_mov_b32 m0, s28
	s_nop 0
	global_load_lds_dwordx4 v208, s[24:25]
	s_mov_b32 m0, s29
	s_nop 0
	global_load_lds_dwordx4 v206, s[24:25]
	ds_read_b128 v[66:69], v198 offset:32768
	ds_read_b128 v[78:81], v198 offset:33792
	ds_read_b128 v[86:89], v198 offset:34816
	ds_read_b128 v[98:101], v198 offset:35840
	ds_read_b128 v[106:109], v198 offset:49152
	ds_read_b128 v[118:121], v198 offset:50176
	ds_read_b128 v[130:133], v198 offset:51200
	ds_read_b128 v[142:145], v198 offset:52224
	ds_read_b128 v[150:153], v234 offset:32768
	ds_read_b128 v[154:157], v234 offset:33792
	ds_read_b128 v[158:161], v234 offset:34816
	ds_read_b128 v[162:165], v234 offset:35840
	ds_read_b128 v[170:173], v234 offset:36864
	ds_read_b128 v[174:177], v234 offset:37888
	ds_read_b128 v[178:181], v234 offset:38912
	ds_read_b128 v[190:193], v234 offset:39936
	s_add_i32 s49, 0, 0x18000
	s_add_i32 s50, 0, 0x1c000
	s_add_u32 s18, s24, 0x160000
	s_addc_u32 s19, s25, 0
	s_mov_b32 m0, s33
	s_nop 0
	global_load_lds_dwordx4 v208, s[18:19]
	s_mov_b32 m0, s37
	s_nop 0
	global_load_lds_dwordx4 v206, s[18:19]
	s_waitcnt vmcnt(8)
	s_waitcnt lgkmcnt(0)
	v_mfma_f32_16x16x32_bf16 v[186:189], v[66:69], v[150:153], v[186:189]
	v_mfma_f32_16x16x32_bf16 v[186:189], v[78:81], v[154:157], v[186:189]
	s_barrier
	s_setprio 1
	v_mfma_f32_16x16x32_bf16 v[182:185], v[98:101], v[154:157], v[182:185]
	v_mfma_f32_16x16x32_bf16 v[182:185], v[86:89], v[150:153], v[182:185]
	v_mfma_f32_16x16x32_bf16 v[134:137], v[86:89], v[158:161], v[134:137]
	v_mfma_f32_16x16x32_bf16 v[134:137], v[98:101], v[162:165], v[134:137]
	v_mfma_f32_16x16x32_bf16 v[138:141], v[78:81], v[162:165], v[138:141]
	v_mfma_f32_16x16x32_bf16 v[138:141], v[66:69], v[158:161], v[138:141]
	v_mfma_f32_16x16x32_bf16 v[114:117], v[66:69], v[170:173], v[114:117]
	v_mfma_f32_16x16x32_bf16 v[114:117], v[78:81], v[174:177], v[114:117]
	v_mfma_f32_16x16x32_bf16 v[110:113], v[98:101], v[174:177], v[110:113]
	v_mfma_f32_16x16x32_bf16 v[110:113], v[86:89], v[170:173], v[110:113]
	v_mfma_f32_16x16x32_bf16 v[82:85], v[86:89], v[178:181], v[82:85]
	v_mfma_f32_16x16x32_bf16 v[82:85], v[98:101], v[190:193], v[82:85]
	v_mfma_f32_16x16x32_bf16 v[90:93], v[78:81], v[190:193], v[90:93]
	v_mfma_f32_16x16x32_bf16 v[90:93], v[66:69], v[178:181], v[90:93]
	v_mfma_f32_16x16x32_bf16 v[166:169], v[106:109], v[150:153], v[166:169]
	v_mfma_f32_16x16x32_bf16 v[166:169], v[118:121], v[154:157], v[166:169]
	v_mfma_f32_16x16x32_bf16 v[146:149], v[142:145], v[154:157], v[146:149]
	v_mfma_f32_16x16x32_bf16 v[146:149], v[130:133], v[150:153], v[146:149]
	v_mfma_f32_16x16x32_bf16 v[122:125], v[130:133], v[158:161], v[122:125]
	v_mfma_f32_16x16x32_bf16 v[122:125], v[142:145], v[162:165], v[122:125]
	v_mfma_f32_16x16x32_bf16 v[126:129], v[118:121], v[162:165], v[126:129]
	v_mfma_f32_16x16x32_bf16 v[126:129], v[106:109], v[158:161], v[126:129]
	v_mfma_f32_16x16x32_bf16 v[102:105], v[106:109], v[170:173], v[102:105]
	v_mfma_f32_16x16x32_bf16 v[102:105], v[118:121], v[174:177], v[102:105]
	v_mfma_f32_16x16x32_bf16 v[94:97], v[142:145], v[174:177], v[94:97]
	v_mfma_f32_16x16x32_bf16 v[94:97], v[130:133], v[170:173], v[94:97]
	v_mfma_f32_16x16x32_bf16 v[70:73], v[130:133], v[178:181], v[70:73]
	v_mfma_f32_16x16x32_bf16 v[70:73], v[142:145], v[190:193], v[70:73]
	v_mfma_f32_16x16x32_bf16 v[74:77], v[118:121], v[190:193], v[74:77]
	v_mfma_f32_16x16x32_bf16 v[74:77], v[106:109], v[178:181], v[74:77]
	s_setprio 0
	s_barrier
	ds_read_b128 v[150:153], v234 offset:49152
	ds_read_b128 v[154:157], v234 offset:50176
	ds_read_b128 v[158:161], v234 offset:51200
	ds_read_b128 v[162:165], v234 offset:52224
	ds_read_b128 v[170:173], v234 offset:53248
	ds_read_b128 v[174:177], v234 offset:54272
	ds_read_b128 v[178:181], v234 offset:55296
	ds_read_b128 v[190:193], v234 offset:56320
	s_add_i32 s18, s49, s26
	s_add_u32 vcc_lo, s22, s94
	s_addc_u32 vcc_hi, s23, s95
	s_mov_b32 m0, s18
	s_nop 0
	global_load_lds_dwordx4 v194, vcc
	s_add_i32 m0, s18, 0x2000
	s_add_u32 s18, s22, 0x160080
	s_addc_u32 s19, s23, 0
	s_add_i32 s22, s50, s26
	global_load_lds_dwordx4 v204, vcc
	s_mov_b32 m0, s22
	s_nop 0
	global_load_lds_dwordx4 v194, s[18:19]
	s_add_i32 m0, s22, 0x2000
	s_nop 0
	global_load_lds_dwordx4 v204, s[18:19]
	s_waitcnt vmcnt(6)
	s_waitcnt lgkmcnt(0)
	v_mfma_f32_16x16x32_bf16 v[62:65], v[66:69], v[150:153], v[62:65]
	v_mfma_f32_16x16x32_bf16 v[62:65], v[78:81], v[154:157], v[62:65]
	s_barrier
	s_setprio 1
	v_mfma_f32_16x16x32_bf16 v[58:61], v[98:101], v[154:157], v[58:61]
	v_mfma_f32_16x16x32_bf16 v[58:61], v[86:89], v[150:153], v[58:61]
	v_mfma_f32_16x16x32_bf16 v[42:45], v[86:89], v[158:161], v[42:45]
	v_mfma_f32_16x16x32_bf16 v[42:45], v[98:101], v[162:165], v[42:45]
	v_mfma_f32_16x16x32_bf16 v[46:49], v[78:81], v[162:165], v[46:49]
	v_mfma_f32_16x16x32_bf16 v[46:49], v[66:69], v[158:161], v[46:49]
	v_mfma_f32_16x16x32_bf16 v[30:33], v[66:69], v[170:173], v[30:33]
	v_mfma_f32_16x16x32_bf16 v[30:33], v[78:81], v[174:177], v[30:33]
	v_mfma_f32_16x16x32_bf16 v[26:29], v[98:101], v[174:177], v[26:29]
	v_mfma_f32_16x16x32_bf16 v[26:29], v[86:89], v[170:173], v[26:29]
	v_mfma_f32_16x16x32_bf16 v[10:13], v[86:89], v[178:181], v[10:13]
	v_mfma_f32_16x16x32_bf16 v[10:13], v[98:101], v[190:193], v[10:13]
	s_add_i32 s48, s48, 2
	v_mfma_f32_16x16x32_bf16 v[14:17], v[78:81], v[190:193], v[14:17]
	v_mfma_f32_16x16x32_bf16 v[14:17], v[66:69], v[178:181], v[14:17]
	s_add_u32 s46, s46, 0x100
	v_mfma_f32_16x16x32_bf16 v[54:57], v[106:109], v[150:153], v[54:57]
	v_mfma_f32_16x16x32_bf16 v[54:57], v[118:121], v[154:157], v[54:57]
	s_addc_u32 s47, s47, 0
	v_mfma_f32_16x16x32_bf16 v[50:53], v[142:145], v[154:157], v[50:53]
	v_mfma_f32_16x16x32_bf16 v[50:53], v[130:133], v[150:153], v[50:53]
	s_cmpk_gt_u32 s48, 0x55
	v_mfma_f32_16x16x32_bf16 v[34:37], v[130:133], v[158:161], v[34:37]
	v_mfma_f32_16x16x32_bf16 v[34:37], v[142:145], v[162:165], v[34:37]
	s_mov_b64 s[18:19], s[20:21]
	v_mfma_f32_16x16x32_bf16 v[38:41], v[118:121], v[162:165], v[38:41]
	v_mfma_f32_16x16x32_bf16 v[38:41], v[106:109], v[158:161], v[38:41]
	v_mfma_f32_16x16x32_bf16 v[22:25], v[106:109], v[170:173], v[22:25]
	v_mfma_f32_16x16x32_bf16 v[22:25], v[118:121], v[174:177], v[22:25]
	v_mfma_f32_16x16x32_bf16 v[18:21], v[142:145], v[174:177], v[18:21]
	v_mfma_f32_16x16x32_bf16 v[18:21], v[130:133], v[170:173], v[18:21]
	v_mfma_f32_16x16x32_bf16 v[2:5], v[130:133], v[178:181], v[2:5]
	v_mfma_f32_16x16x32_bf16 v[2:5], v[142:145], v[190:193], v[2:5]
	v_mfma_f32_16x16x32_bf16 v[6:9], v[118:121], v[190:193], v[6:9]
	v_mfma_f32_16x16x32_bf16 v[6:9], v[106:109], v[178:181], v[6:9]
	s_setprio 0
	s_barrier
	s_cbranch_scc0 .LBB0_1441
	s_and_b64 vcc, exec, s[14:15]
	s_cbranch_vccz .LBB0_1444
	s_barrier

.LBB0_1511:
	s_add_u32 vcc_lo, s18, 0xffea0000
	s_addc_u32 vcc_hi, s19, -1
	s_mov_b32 m0, s44
	s_nop 0
	global_load_lds_dwordx4 v210, vcc
	s_mov_b32 m0, s45
	s_nop 0
	global_load_lds_dwordx4 v212, vcc
	ds_read_b128 v[130:133], v235
	ds_read_b128 v[134:137], v235 offset:1024
	ds_read_b128 v[138:141], v235 offset:2048
	ds_read_b128 v[142:145], v235 offset:3072
	ds_read_b128 v[146:149], v235 offset:16384
	ds_read_b128 v[150:153], v235 offset:17408
	ds_read_b128 v[154:157], v235 offset:18432
	ds_read_b128 v[158:161], v235 offset:19456
	ds_read_b128 v[162:165], v237
	ds_read_b128 v[166:169], v237 offset:1024
	ds_read_b128 v[170:173], v237 offset:2048
	ds_read_b128 v[174:177], v237 offset:3072
	ds_read_b128 v[178:181], v237 offset:4096
	ds_read_b128 v[182:185], v237 offset:5120
	ds_read_b128 v[186:189], v237 offset:6144
	ds_read_b128 v[190:193], v237 offset:7168
	s_add_i32 s55, s26, 2
	s_add_u32 s24, s18, 0x100
	s_addc_u32 s25, s19, 0
	s_add_i32 s56, 0, 0x10000
	s_cmp_eq_u32 s15, s26
	s_cselect_b32 s29, s7, s25
	s_cselect_b32 s28, s6, s24
	s_cselect_b32 s27, s17, s54
	s_cselect_b32 s26, s16, s23
	s_add_i32 s57, 0, 0x14000
	s_add_i32 m0, s40, 0xc000
	s_nop 0
	global_load_lds_dwordx4 v210, s[18:19]
	s_add_i32 m0, s40, 0xe000
	s_nop 0
	global_load_lds_dwordx4 v212, s[18:19]
	s_waitcnt vmcnt(8)
	s_waitcnt lgkmcnt(0)
	v_mfma_f32_16x16x32_bf16 v[126:129], v[130:133], v[162:165], v[126:129]
	v_mfma_f32_16x16x32_bf16 v[126:129], v[134:137], v[166:169], v[126:129]
	s_barrier
	s_setprio 1
	v_mfma_f32_16x16x32_bf16 v[122:125], v[142:145], v[166:169], v[122:125]
	v_mfma_f32_16x16x32_bf16 v[122:125], v[138:141], v[162:165], v[122:125]
	v_mfma_f32_16x16x32_bf16 v[106:109], v[138:141], v[170:173], v[106:109]
	v_mfma_f32_16x16x32_bf16 v[106:109], v[142:145], v[174:177], v[106:109]
	v_mfma_f32_16x16x32_bf16 v[110:113], v[134:137], v[174:177], v[110:113]
	v_mfma_f32_16x16x32_bf16 v[110:113], v[130:133], v[170:173], v[110:113]
	v_mfma_f32_16x16x32_bf16 v[94:97], v[130:133], v[178:181], v[94:97]
	v_mfma_f32_16x16x32_bf16 v[94:97], v[134:137], v[182:185], v[94:97]
	v_mfma_f32_16x16x32_bf16 v[90:93], v[142:145], v[182:185], v[90:93]
	v_mfma_f32_16x16x32_bf16 v[90:93], v[138:141], v[178:181], v[90:93]
	v_mfma_f32_16x16x32_bf16 v[74:77], v[138:141], v[186:189], v[74:77]
	v_mfma_f32_16x16x32_bf16 v[74:77], v[142:145], v[190:193], v[74:77]
	v_mfma_f32_16x16x32_bf16 v[78:81], v[134:137], v[190:193], v[78:81]
	v_mfma_f32_16x16x32_bf16 v[78:81], v[130:133], v[186:189], v[78:81]
	v_mfma_f32_16x16x32_bf16 v[118:121], v[146:149], v[162:165], v[118:121]
	v_mfma_f32_16x16x32_bf16 v[118:121], v[150:153], v[166:169], v[118:121]
	v_mfma_f32_16x16x32_bf16 v[114:117], v[158:161], v[166:169], v[114:117]
	v_mfma_f32_16x16x32_bf16 v[114:117], v[154:157], v[162:165], v[114:117]
	v_mfma_f32_16x16x32_bf16 v[98:101], v[154:157], v[170:173], v[98:101]
	v_mfma_f32_16x16x32_bf16 v[98:101], v[158:161], v[174:177], v[98:101]
	v_mfma_f32_16x16x32_bf16 v[102:105], v[150:153], v[174:177], v[102:105]
	v_mfma_f32_16x16x32_bf16 v[102:105], v[146:149], v[170:173], v[102:105]
	v_mfma_f32_16x16x32_bf16 v[86:89], v[146:149], v[178:181], v[86:89]
	v_mfma_f32_16x16x32_bf16 v[86:89], v[150:153], v[182:185], v[86:89]
	v_mfma_f32_16x16x32_bf16 v[82:85], v[158:161], v[182:185], v[82:85]
	v_mfma_f32_16x16x32_bf16 v[82:85], v[154:157], v[178:181], v[82:85]
	v_mfma_f32_16x16x32_bf16 v[66:69], v[154:157], v[186:189], v[66:69]
	v_mfma_f32_16x16x32_bf16 v[66:69], v[158:161], v[190:193], v[66:69]
	v_mfma_f32_16x16x32_bf16 v[70:73], v[150:153], v[190:193], v[70:73]
	v_mfma_f32_16x16x32_bf16 v[70:73], v[146:149], v[186:189], v[70:73]
	s_setprio 0
	s_barrier
	ds_read_b128 v[162:165], v237 offset:16384
	ds_read_b128 v[166:169], v237 offset:17408
	ds_read_b128 v[170:173], v237 offset:18432
	ds_read_b128 v[174:177], v237 offset:19456
	ds_read_b128 v[178:181], v237 offset:20480
	ds_read_b128 v[182:185], v237 offset:21504
	ds_read_b128 v[186:189], v237 offset:22528
	ds_read_b128 v[190:193], v237 offset:23552
	s_add_i32 s18, s56, s39
	s_mov_b32 m0, s18
	s_nop 0
	global_load_lds_dwordx4 v194, s[26:27]
	s_add_i32 m0, s18, 0x2000
	s_add_u32 s18, s26, 0x160000
	s_addc_u32 s19, s27, 0
	s_add_i32 s56, s57, s39
	global_load_lds_dwordx4 v208, s[26:27]
	s_mov_b32 m0, s56
	s_nop 0
	global_load_lds_dwordx4 v194, s[18:19]
	s_add_i32 m0, s56, 0x2000
	s_nop 0
	global_load_lds_dwordx4 v208, s[18:19]
	s_waitcnt vmcnt(6)
	s_waitcnt lgkmcnt(0)
	v_mfma_f32_16x16x32_bf16 v[62:65], v[130:133], v[162:165], v[62:65]
	v_mfma_f32_16x16x32_bf16 v[62:65], v[134:137], v[166:169], v[62:65]
	s_barrier
	s_setprio 1
	v_mfma_f32_16x16x32_bf16 v[58:61], v[142:145], v[166:169], v[58:61]
	v_mfma_f32_16x16x32_bf16 v[58:61], v[138:141], v[162:165], v[58:61]
	v_mfma_f32_16x16x32_bf16 v[42:45], v[138:141], v[170:173], v[42:45]
	v_mfma_f32_16x16x32_bf16 v[42:45], v[142:145], v[174:177], v[42:45]
	v_mfma_f32_16x16x32_bf16 v[46:49], v[134:137], v[174:177], v[46:49]
	v_mfma_f32_16x16x32_bf16 v[46:49], v[130:133], v[170:173], v[46:49]
	v_mfma_f32_16x16x32_bf16 v[30:33], v[130:133], v[178:181], v[30:33]
	v_mfma_f32_16x16x32_bf16 v[30:33], v[134:137], v[182:185], v[30:33]
	v_mfma_f32_16x16x32_bf16 v[26:29], v[142:145], v[182:185], v[26:29]
	v_mfma_f32_16x16x32_bf16 v[26:29], v[138:141], v[178:181], v[26:29]
	v_mfma_f32_16x16x32_bf16 v[10:13], v[138:141], v[186:189], v[10:13]
	v_mfma_f32_16x16x32_bf16 v[10:13], v[142:145], v[190:193], v[10:13]
	v_mfma_f32_16x16x32_bf16 v[14:17], v[134:137], v[190:193], v[14:17]
	v_mfma_f32_16x16x32_bf16 v[14:17], v[130:133], v[186:189], v[14:17]
	v_mfma_f32_16x16x32_bf16 v[54:57], v[146:149], v[162:165], v[54:57]
	v_mfma_f32_16x16x32_bf16 v[54:57], v[150:153], v[166:169], v[54:57]
	v_mfma_f32_16x16x32_bf16 v[50:53], v[158:161], v[166:169], v[50:53]
	v_mfma_f32_16x16x32_bf16 v[50:53], v[154:157], v[162:165], v[50:53]
	v_mfma_f32_16x16x32_bf16 v[34:37], v[154:157], v[170:173], v[34:37]
	v_mfma_f32_16x16x32_bf16 v[34:37], v[158:161], v[174:177], v[34:37]
	v_mfma_f32_16x16x32_bf16 v[38:41], v[150:153], v[174:177], v[38:41]
	v_mfma_f32_16x16x32_bf16 v[38:41], v[146:149], v[170:173], v[38:41]
	v_mfma_f32_16x16x32_bf16 v[22:25], v[146:149], v[178:181], v[22:25]
	v_mfma_f32_16x16x32_bf16 v[22:25], v[150:153], v[182:185], v[22:25]
	v_mfma_f32_16x16x32_bf16 v[18:21], v[158:161], v[182:185], v[18:21]
	v_mfma_f32_16x16x32_bf16 v[18:21], v[154:157], v[178:181], v[18:21]
	v_mfma_f32_16x16x32_bf16 v[2:5], v[154:157], v[186:189], v[2:5]
	v_mfma_f32_16x16x32_bf16 v[2:5], v[158:161], v[190:193], v[2:5]
	v_mfma_f32_16x16x32_bf16 v[6:9], v[150:153], v[190:193], v[6:9]
	v_mfma_f32_16x16x32_bf16 v[6:9], v[146:149], v[186:189], v[6:9]
	s_setprio 0
	s_barrier
	s_mov_b32 m0, s40
	s_nop 0
	global_load_lds_dwordx4 v204, s[28:29]
	s_mov_b32 m0, s41
	s_nop 0
	global_load_lds_dwordx4 v206, s[28:29]
	ds_read_b128 v[130:133], v235 offset:32768
	ds_read_b128 v[134:137], v235 offset:33792
	ds_read_b128 v[138:141], v235 offset:34816
	ds_read_b128 v[142:145], v235 offset:35840
	ds_read_b128 v[146:149], v235 offset:49152
	ds_read_b128 v[150:153], v235 offset:50176
	ds_read_b128 v[154:157], v235 offset:51200
	ds_read_b128 v[158:161], v235 offset:52224
	ds_read_b128 v[162:165], v237 offset:32768
	ds_read_b128 v[166:169], v237 offset:33792
	ds_read_b128 v[170:173], v237 offset:34816
	ds_read_b128 v[174:177], v237 offset:35840
	ds_read_b128 v[178:181], v237 offset:36864
	ds_read_b128 v[182:185], v237 offset:37888
	ds_read_b128 v[186:189], v237 offset:38912
	ds_read_b128 v[190:193], v237 offset:39936
	s_add_i32 s56, 0, 0x18000
	s_add_i32 s57, 0, 0x1c000
	s_add_u32 s18, s28, 0x160000
	s_addc_u32 s19, s29, 0
	s_mov_b32 m0, s42
	s_nop 0
	global_load_lds_dwordx4 v204, s[18:19]
	s_mov_b32 m0, s43
	s_nop 0
	global_load_lds_dwordx4 v206, s[18:19]
	s_waitcnt vmcnt(8)
	s_waitcnt lgkmcnt(0)
	v_mfma_f32_16x16x32_bf16 v[126:129], v[130:133], v[162:165], v[126:129]
	v_mfma_f32_16x16x32_bf16 v[126:129], v[134:137], v[166:169], v[126:129]
	s_barrier
	s_setprio 1
	v_mfma_f32_16x16x32_bf16 v[122:125], v[142:145], v[166:169], v[122:125]
	v_mfma_f32_16x16x32_bf16 v[122:125], v[138:141], v[162:165], v[122:125]
	v_mfma_f32_16x16x32_bf16 v[106:109], v[138:141], v[170:173], v[106:109]
	v_mfma_f32_16x16x32_bf16 v[106:109], v[142:145], v[174:177], v[106:109]
	v_mfma_f32_16x16x32_bf16 v[110:113], v[134:137], v[174:177], v[110:113]
	v_mfma_f32_16x16x32_bf16 v[110:113], v[130:133], v[170:173], v[110:113]
	v_mfma_f32_16x16x32_bf16 v[94:97], v[130:133], v[178:181], v[94:97]
	v_mfma_f32_16x16x32_bf16 v[94:97], v[134:137], v[182:185], v[94:97]
	v_mfma_f32_16x16x32_bf16 v[90:93], v[142:145], v[182:185], v[90:93]
	v_mfma_f32_16x16x32_bf16 v[90:93], v[138:141], v[178:181], v[90:93]
	v_mfma_f32_16x16x32_bf16 v[74:77], v[138:141], v[186:189], v[74:77]
	v_mfma_f32_16x16x32_bf16 v[74:77], v[142:145], v[190:193], v[74:77]
	v_mfma_f32_16x16x32_bf16 v[78:81], v[134:137], v[190:193], v[78:81]
	v_mfma_f32_16x16x32_bf16 v[78:81], v[130:133], v[186:189], v[78:81]
	v_mfma_f32_16x16x32_bf16 v[118:121], v[146:149], v[162:165], v[118:121]
	v_mfma_f32_16x16x32_bf16 v[118:121], v[150:153], v[166:169], v[118:121]
	v_mfma_f32_16x16x32_bf16 v[114:117], v[158:161], v[166:169], v[114:117]
	v_mfma_f32_16x16x32_bf16 v[114:117], v[154:157], v[162:165], v[114:117]
	v_mfma_f32_16x16x32_bf16 v[98:101], v[154:157], v[170:173], v[98:101]
	v_mfma_f32_16x16x32_bf16 v[98:101], v[158:161], v[174:177], v[98:101]
	v_mfma_f32_16x16x32_bf16 v[102:105], v[150:153], v[174:177], v[102:105]
	v_mfma_f32_16x16x32_bf16 v[102:105], v[146:149], v[170:173], v[102:105]
	v_mfma_f32_16x16x32_bf16 v[86:89], v[146:149], v[178:181], v[86:89]
	v_mfma_f32_16x16x32_bf16 v[86:89], v[150:153], v[182:185], v[86:89]
	v_mfma_f32_16x16x32_bf16 v[82:85], v[158:161], v[182:185], v[82:85]
	v_mfma_f32_16x16x32_bf16 v[82:85], v[154:157], v[178:181], v[82:85]
	v_mfma_f32_16x16x32_bf16 v[66:69], v[154:157], v[186:189], v[66:69]
	v_mfma_f32_16x16x32_bf16 v[66:69], v[158:161], v[190:193], v[66:69]
	v_mfma_f32_16x16x32_bf16 v[70:73], v[150:153], v[190:193], v[70:73]
	v_mfma_f32_16x16x32_bf16 v[70:73], v[146:149], v[186:189], v[70:73]
	s_setprio 0
	s_barrier
	ds_read_b128 v[162:165], v237 offset:49152
	ds_read_b128 v[166:169], v237 offset:50176
	ds_read_b128 v[170:173], v237 offset:51200
	ds_read_b128 v[174:177], v237 offset:52224
	ds_read_b128 v[178:181], v237 offset:53248
	ds_read_b128 v[182:185], v237 offset:54272
	ds_read_b128 v[186:189], v237 offset:55296
	ds_read_b128 v[190:193], v237 offset:56320
	s_add_i32 s18, s56, s39
	s_add_u32 vcc_lo, s26, s94
	s_addc_u32 vcc_hi, s27, s95
	s_mov_b32 m0, s18
	s_nop 0
	global_load_lds_dwordx4 v194, vcc
	s_add_i32 m0, s18, 0x2000
	s_add_u32 s18, s26, 0x160080
	s_addc_u32 s19, s27, 0
	s_add_i32 s26, s57, s39
	global_load_lds_dwordx4 v208, vcc
	s_mov_b32 m0, s26
	s_nop 0
	global_load_lds_dwordx4 v194, s[18:19]
	s_add_i32 m0, s26, 0x2000
	s_nop 0
	global_load_lds_dwordx4 v208, s[18:19]
	s_waitcnt vmcnt(6)
	s_waitcnt lgkmcnt(0)
	v_mfma_f32_16x16x32_bf16 v[62:65], v[130:133], v[162:165], v[62:65]
	v_mfma_f32_16x16x32_bf16 v[62:65], v[134:137], v[166:169], v[62:65]
	s_barrier
	s_setprio 1
	v_mfma_f32_16x16x32_bf16 v[58:61], v[142:145], v[166:169], v[58:61]
	v_mfma_f32_16x16x32_bf16 v[58:61], v[138:141], v[162:165], v[58:61]
	v_mfma_f32_16x16x32_bf16 v[42:45], v[138:141], v[170:173], v[42:45]
	v_mfma_f32_16x16x32_bf16 v[42:45], v[142:145], v[174:177], v[42:45]
	v_mfma_f32_16x16x32_bf16 v[46:49], v[134:137], v[174:177], v[46:49]
	v_mfma_f32_16x16x32_bf16 v[46:49], v[130:133], v[170:173], v[46:49]
	v_mfma_f32_16x16x32_bf16 v[30:33], v[130:133], v[178:181], v[30:33]
	v_mfma_f32_16x16x32_bf16 v[30:33], v[134:137], v[182:185], v[30:33]
	v_mfma_f32_16x16x32_bf16 v[26:29], v[142:145], v[182:185], v[26:29]
	v_mfma_f32_16x16x32_bf16 v[26:29], v[138:141], v[178:181], v[26:29]
	v_mfma_f32_16x16x32_bf16 v[10:13], v[138:141], v[186:189], v[10:13]
	v_mfma_f32_16x16x32_bf16 v[10:13], v[142:145], v[190:193], v[10:13]
	s_add_u32 s23, s23, 0x100
	v_mfma_f32_16x16x32_bf16 v[14:17], v[134:137], v[190:193], v[14:17]
	v_mfma_f32_16x16x32_bf16 v[14:17], v[130:133], v[186:189], v[14:17]
	s_addc_u32 s54, s54, 0
	v_mfma_f32_16x16x32_bf16 v[54:57], v[146:149], v[162:165], v[54:57]
	v_mfma_f32_16x16x32_bf16 v[54:57], v[150:153], v[166:169], v[54:57]
	s_cmp_ge_i32 s55, s21
	v_mfma_f32_16x16x32_bf16 v[50:53], v[158:161], v[166:169], v[50:53]
	v_mfma_f32_16x16x32_bf16 v[50:53], v[154:157], v[162:165], v[50:53]
	s_mov_b64 s[18:19], s[24:25]
	v_mfma_f32_16x16x32_bf16 v[34:37], v[154:157], v[170:173], v[34:37]
	v_mfma_f32_16x16x32_bf16 v[34:37], v[158:161], v[174:177], v[34:37]
	s_mov_b32 s26, s55
	v_mfma_f32_16x16x32_bf16 v[38:41], v[150:153], v[174:177], v[38:41]
	v_mfma_f32_16x16x32_bf16 v[38:41], v[146:149], v[170:173], v[38:41]
	v_mfma_f32_16x16x32_bf16 v[22:25], v[146:149], v[178:181], v[22:25]
	v_mfma_f32_16x16x32_bf16 v[22:25], v[150:153], v[182:185], v[22:25]
	v_mfma_f32_16x16x32_bf16 v[18:21], v[158:161], v[182:185], v[18:21]
	v_mfma_f32_16x16x32_bf16 v[18:21], v[154:157], v[178:181], v[18:21]
	v_mfma_f32_16x16x32_bf16 v[2:5], v[154:157], v[186:189], v[2:5]
	v_mfma_f32_16x16x32_bf16 v[2:5], v[158:161], v[190:193], v[2:5]
	v_mfma_f32_16x16x32_bf16 v[6:9], v[150:153], v[190:193], v[6:9]
	v_mfma_f32_16x16x32_bf16 v[6:9], v[146:149], v[186:189], v[6:9]
	s_setprio 0
	s_barrier
	s_cbranch_scc0 .LBB0_1511
	s_and_b64 vcc, exec, s[12:13]
	s_cbranch_vccz .LBB0_1514
